# branch-merge and residual epilogues (P6, P7, P11): accumulators lane-transposed in place (ds_bpermute) so their row loads and stores coalesce
# speedup vs baseline: 1.0436x; 1.0070x over previous
.LBB0_765:
	v_mbcnt_lo_u32_b32 v232, -1, 0
	v_mbcnt_hi_u32_b32 v232, -1, v232
	v_and_b32_e32 v233, 3, v232
	v_lshrrev_b32_e32 v234, 2, v232
	v_lshl_add_u32 v235, v233, 4, v234
	v_lshlrev_b32_e32 v235, 2, v235
	v_readfirstlane_b32 s28, v158
	v_readfirstlane_b32 s29, v160
	s_lshl_b32 s30, s59, 8
	s_add_i32 s28, s30, s28
	s_lshl_b32 s30, s60, 8
	s_or_b32 s29, s30, s29
	v_add_u32_e32 v234, s28, v234
	v_lshl_add_u32 v233, v233, 3, s29
	v_lshlrev_b32_e32 v233, 1, v233
	v_mul_u32_u24_e32 v236, 0x1800, v234
	v_add_u32_e32 v138, v236, v233
	v_lshl_add_u32 v139, v234, 11, v233
	s_mov_b32 s62, 0xffff0000
	s_cmp_lg_u32 s36, 0
	s_cbranch_scc0 .Lp6_first
	s_add_u32 s28, s10, 0x0
	s_addc_u32 s29, s11, 0
	s_add_u32 s30, s8, 0x0
	s_addc_u32 s31, s9, 0
	global_load_dwordx4 v[130:133], v138, s[28:29]
	global_load_dwordx4 v[150:153], v139, s[30:31]
	global_load_dwordx4 v[134:137], v138, s[28:29] offset:256
	global_load_dwordx4 v[154:157], v139, s[30:31] offset:256
	s_add_u32 s28, s10, 0x18000
	s_addc_u32 s29, s11, 0
	s_add_u32 s30, s8, 0x8000
	s_addc_u32 s31, s9, 0
	global_load_dwordx4 v[162:165], v138, s[28:29]
	global_load_dwordx4 v[170:173], v139, s[30:31]
	global_load_dwordx4 v[166:169], v138, s[28:29] offset:256
	global_load_dwordx4 v[174:177], v139, s[30:31] offset:256
	s_add_u32 s28, s10, 0x30000
	s_addc_u32 s29, s11, 0
	s_add_u32 s30, s8, 0x10000
	s_addc_u32 s31, s9, 0
	global_load_dwordx4 v[178:181], v138, s[28:29]
	global_load_dwordx4 v[190:193], v139, s[30:31]
	global_load_dwordx4 v[186:189], v138, s[28:29] offset:256
	global_load_dwordx4 v[212:215], v139, s[30:31] offset:256
	s_add_u32 s28, s10, 0x48000
	s_addc_u32 s29, s11, 0
	s_add_u32 s30, s8, 0x18000
	s_addc_u32 s31, s9, 0
	global_load_dwordx4 v[216:219], v138, s[28:29]
	global_load_dwordx4 v[224:227], v139, s[30:31]
	global_load_dwordx4 v[220:223], v138, s[28:29] offset:256
	global_load_dwordx4 v[228:231], v139, s[30:31] offset:256
	ds_bpermute_b32 v2, v235, v2
	ds_bpermute_b32 v3, v235, v3
	ds_bpermute_b32 v4, v235, v4
	ds_bpermute_b32 v5, v235, v5
	ds_bpermute_b32 v6, v235, v6
	ds_bpermute_b32 v7, v235, v7
	ds_bpermute_b32 v8, v235, v8
	s_waitcnt lgkmcnt(7)
	ds_bpermute_b32 v9, v235, v9
	ds_bpermute_b32 v10, v235, v10
	ds_bpermute_b32 v11, v235, v11
	ds_bpermute_b32 v12, v235, v12
	ds_bpermute_b32 v13, v235, v13
	ds_bpermute_b32 v14, v235, v14
	ds_bpermute_b32 v15, v235, v15
	s_waitcnt lgkmcnt(7)
	ds_bpermute_b32 v16, v235, v16
	ds_bpermute_b32 v17, v235, v17
	ds_bpermute_b32 v18, v235, v18
	ds_bpermute_b32 v19, v235, v19
	ds_bpermute_b32 v20, v235, v20
	ds_bpermute_b32 v21, v235, v21
	ds_bpermute_b32 v22, v235, v22
	s_waitcnt lgkmcnt(7)
	ds_bpermute_b32 v23, v235, v23
	ds_bpermute_b32 v24, v235, v24
	ds_bpermute_b32 v25, v235, v25
	ds_bpermute_b32 v26, v235, v26
	ds_bpermute_b32 v27, v235, v27
	ds_bpermute_b32 v28, v235, v28
	ds_bpermute_b32 v29, v235, v29
	s_waitcnt lgkmcnt(7)
	ds_bpermute_b32 v30, v235, v30
	ds_bpermute_b32 v31, v235, v31
	ds_bpermute_b32 v32, v235, v32
	ds_bpermute_b32 v33, v235, v33
	ds_bpermute_b32 v34, v235, v34
	ds_bpermute_b32 v35, v235, v35
	ds_bpermute_b32 v36, v235, v36
	s_waitcnt lgkmcnt(7)
	ds_bpermute_b32 v37, v235, v37
	ds_bpermute_b32 v38, v235, v38
	ds_bpermute_b32 v39, v235, v39
	ds_bpermute_b32 v40, v235, v40
	ds_bpermute_b32 v41, v235, v41
	ds_bpermute_b32 v42, v235, v42
	ds_bpermute_b32 v43, v235, v43
	s_waitcnt lgkmcnt(7)
	ds_bpermute_b32 v44, v235, v44
	ds_bpermute_b32 v45, v235, v45
	ds_bpermute_b32 v46, v235, v46
	ds_bpermute_b32 v47, v235, v47
	ds_bpermute_b32 v48, v235, v48
	ds_bpermute_b32 v49, v235, v49
	ds_bpermute_b32 v50, v235, v50
	s_waitcnt lgkmcnt(7)
	ds_bpermute_b32 v51, v235, v51
	ds_bpermute_b32 v52, v235, v52
	ds_bpermute_b32 v53, v235, v53
	ds_bpermute_b32 v54, v235, v54
	ds_bpermute_b32 v55, v235, v55
	ds_bpermute_b32 v56, v235, v56
	ds_bpermute_b32 v57, v235, v57
	s_waitcnt lgkmcnt(7)
	ds_bpermute_b32 v58, v235, v58
	ds_bpermute_b32 v59, v235, v59
	ds_bpermute_b32 v60, v235, v60
	ds_bpermute_b32 v61, v235, v61
	ds_bpermute_b32 v62, v235, v62
	ds_bpermute_b32 v63, v235, v63
	ds_bpermute_b32 v64, v235, v64
	s_waitcnt lgkmcnt(7)
	ds_bpermute_b32 v65, v235, v65
	ds_bpermute_b32 v66, v235, v66
	ds_bpermute_b32 v67, v235, v67
	ds_bpermute_b32 v68, v235, v68
	ds_bpermute_b32 v69, v235, v69
	ds_bpermute_b32 v70, v235, v70
	ds_bpermute_b32 v71, v235, v71
	s_waitcnt lgkmcnt(7)
	ds_bpermute_b32 v72, v235, v72
	ds_bpermute_b32 v73, v235, v73
	ds_bpermute_b32 v74, v235, v74
	ds_bpermute_b32 v75, v235, v75
	ds_bpermute_b32 v76, v235, v76
	ds_bpermute_b32 v77, v235, v77
	ds_bpermute_b32 v78, v235, v78
	s_waitcnt lgkmcnt(7)
	ds_bpermute_b32 v79, v235, v79
	ds_bpermute_b32 v80, v235, v80
	ds_bpermute_b32 v81, v235, v81
	ds_bpermute_b32 v82, v235, v82
	ds_bpermute_b32 v83, v235, v83
	ds_bpermute_b32 v84, v235, v84
	ds_bpermute_b32 v85, v235, v85
	s_waitcnt lgkmcnt(7)
	ds_bpermute_b32 v86, v235, v86
	ds_bpermute_b32 v87, v235, v87
	ds_bpermute_b32 v88, v235, v88
	ds_bpermute_b32 v89, v235, v89
	ds_bpermute_b32 v90, v235, v90
	ds_bpermute_b32 v91, v235, v91
	ds_bpermute_b32 v92, v235, v92
	s_waitcnt lgkmcnt(7)
	ds_bpermute_b32 v93, v235, v93
	ds_bpermute_b32 v94, v235, v94
	ds_bpermute_b32 v95, v235, v95
	ds_bpermute_b32 v96, v235, v96
	ds_bpermute_b32 v97, v235, v97
	ds_bpermute_b32 v98, v235, v98
	ds_bpermute_b32 v99, v235, v99
	s_waitcnt lgkmcnt(7)
	ds_bpermute_b32 v100, v235, v100
	ds_bpermute_b32 v101, v235, v101
	ds_bpermute_b32 v102, v235, v102
	ds_bpermute_b32 v103, v235, v103
	ds_bpermute_b32 v104, v235, v104
	ds_bpermute_b32 v105, v235, v105
	ds_bpermute_b32 v106, v235, v106
	s_waitcnt lgkmcnt(7)
	ds_bpermute_b32 v107, v235, v107
	ds_bpermute_b32 v108, v235, v108
	ds_bpermute_b32 v109, v235, v109
	ds_bpermute_b32 v110, v235, v110
	ds_bpermute_b32 v111, v235, v111
	ds_bpermute_b32 v112, v235, v112
	ds_bpermute_b32 v113, v235, v113
	s_waitcnt lgkmcnt(7)
	ds_bpermute_b32 v114, v235, v114
	ds_bpermute_b32 v115, v235, v115
	ds_bpermute_b32 v116, v235, v116
	ds_bpermute_b32 v117, v235, v117
	ds_bpermute_b32 v118, v235, v118
	ds_bpermute_b32 v119, v235, v119
	ds_bpermute_b32 v120, v235, v120
	s_waitcnt lgkmcnt(7)
	ds_bpermute_b32 v121, v235, v121
	ds_bpermute_b32 v122, v235, v122
	ds_bpermute_b32 v123, v235, v123
	ds_bpermute_b32 v124, v235, v124
	ds_bpermute_b32 v125, v235, v125
	ds_bpermute_b32 v126, v235, v126
	ds_bpermute_b32 v127, v235, v127
	s_waitcnt lgkmcnt(7)
	ds_bpermute_b32 v128, v235, v128
	ds_bpermute_b32 v129, v235, v129
	s_waitcnt lgkmcnt(0)
	s_waitcnt vmcnt(14)
	v_lshlrev_b32_e32 v194, 16, v130
	v_and_b32_e32 v195, s62, v130
	v_lshlrev_b32_e32 v234, 16, v150
	v_and_b32_e32 v235, s62, v150
	v_pk_fma_f32 v[126:127], v[126:127], v[194:195], v[234:235]
	v_lshlrev_b32_e32 v232, 16, v131
	v_and_b32_e32 v233, s62, v131
	v_lshlrev_b32_e32 v236, 16, v151
	v_and_b32_e32 v237, s62, v151
	v_pk_fma_f32 v[128:129], v[128:129], v[232:233], v[236:237]
	v_lshlrev_b32_e32 v194, 16, v132
	v_and_b32_e32 v195, s62, v132
	v_lshlrev_b32_e32 v234, 16, v152
	v_and_b32_e32 v235, s62, v152
	v_pk_fma_f32 v[122:123], v[122:123], v[194:195], v[234:235]
	v_lshlrev_b32_e32 v232, 16, v133
	v_and_b32_e32 v233, s62, v133
	v_lshlrev_b32_e32 v236, 16, v153
	v_and_b32_e32 v237, s62, v153
	v_pk_fma_f32 v[124:125], v[124:125], v[232:233], v[236:237]
	v_cvt_pk_bf16_f32 v126, v126, v127
	v_cvt_pk_bf16_f32 v127, v128, v129
	v_cvt_pk_bf16_f32 v128, v122, v123
	v_cvt_pk_bf16_f32 v129, v124, v125
	s_waitcnt vmcnt(12)
	v_lshlrev_b32_e32 v194, 16, v134
	v_and_b32_e32 v195, s62, v134
	v_lshlrev_b32_e32 v234, 16, v154
	v_and_b32_e32 v235, s62, v154
	v_pk_fma_f32 v[118:119], v[118:119], v[194:195], v[234:235]
	v_lshlrev_b32_e32 v232, 16, v135
	v_and_b32_e32 v233, s62, v135
	v_lshlrev_b32_e32 v236, 16, v155
	v_and_b32_e32 v237, s62, v155
	v_pk_fma_f32 v[120:121], v[120:121], v[232:233], v[236:237]
	v_lshlrev_b32_e32 v194, 16, v136
	v_and_b32_e32 v195, s62, v136
	v_lshlrev_b32_e32 v234, 16, v156
	v_and_b32_e32 v235, s62, v156
	v_pk_fma_f32 v[114:115], v[114:115], v[194:195], v[234:235]
	v_lshlrev_b32_e32 v232, 16, v137
	v_and_b32_e32 v233, s62, v137
	v_lshlrev_b32_e32 v236, 16, v157
	v_and_b32_e32 v237, s62, v157
	v_pk_fma_f32 v[116:117], v[116:117], v[232:233], v[236:237]
	v_cvt_pk_bf16_f32 v118, v118, v119
	v_cvt_pk_bf16_f32 v119, v120, v121
	v_cvt_pk_bf16_f32 v120, v114, v115
	v_cvt_pk_bf16_f32 v121, v116, v117
	s_add_u32 s28, s10, 0xc0000
	s_addc_u32 s29, s11, 0
	s_add_u32 s30, s8, 0x40000
	s_addc_u32 s31, s9, 0
	global_load_dwordx4 v[130:133], v138, s[28:29]
	global_load_dwordx4 v[150:153], v139, s[30:31]
	global_load_dwordx4 v[134:137], v138, s[28:29] offset:256
	global_load_dwordx4 v[154:157], v139, s[30:31] offset:256
	s_add_u32 s42, s8, 0x0
	s_addc_u32 s43, s9, 0
	global_store_dwordx4 v139, v[126:129], s[42:43]
	global_store_dwordx4 v139, v[118:121], s[42:43] offset:256
	s_waitcnt vmcnt(16)
	v_lshlrev_b32_e32 v194, 16, v162
	v_and_b32_e32 v195, s62, v162
	v_lshlrev_b32_e32 v234, 16, v170
	v_and_b32_e32 v235, s62, v170
	v_pk_fma_f32 v[110:111], v[110:111], v[194:195], v[234:235]
	v_lshlrev_b32_e32 v232, 16, v163
	v_and_b32_e32 v233, s62, v163
	v_lshlrev_b32_e32 v236, 16, v171
	v_and_b32_e32 v237, s62, v171
	v_pk_fma_f32 v[112:113], v[112:113], v[232:233], v[236:237]
	v_lshlrev_b32_e32 v194, 16, v164
	v_and_b32_e32 v195, s62, v164
	v_lshlrev_b32_e32 v234, 16, v172
	v_and_b32_e32 v235, s62, v172
	v_pk_fma_f32 v[106:107], v[106:107], v[194:195], v[234:235]
	v_lshlrev_b32_e32 v232, 16, v165
	v_and_b32_e32 v233, s62, v165
	v_lshlrev_b32_e32 v236, 16, v173
	v_and_b32_e32 v237, s62, v173
	v_pk_fma_f32 v[108:109], v[108:109], v[232:233], v[236:237]
	v_cvt_pk_bf16_f32 v110, v110, v111
	v_cvt_pk_bf16_f32 v111, v112, v113
	v_cvt_pk_bf16_f32 v112, v106, v107
	v_cvt_pk_bf16_f32 v113, v108, v109
	s_waitcnt vmcnt(14)
	v_lshlrev_b32_e32 v194, 16, v166
	v_and_b32_e32 v195, s62, v166
	v_lshlrev_b32_e32 v234, 16, v174
	v_and_b32_e32 v235, s62, v174
	v_pk_fma_f32 v[102:103], v[102:103], v[194:195], v[234:235]
	v_lshlrev_b32_e32 v232, 16, v167
	v_and_b32_e32 v233, s62, v167
	v_lshlrev_b32_e32 v236, 16, v175
	v_and_b32_e32 v237, s62, v175
	v_pk_fma_f32 v[104:105], v[104:105], v[232:233], v[236:237]
	v_lshlrev_b32_e32 v194, 16, v168
	v_and_b32_e32 v195, s62, v168
	v_lshlrev_b32_e32 v234, 16, v176
	v_and_b32_e32 v235, s62, v176
	v_pk_fma_f32 v[98:99], v[98:99], v[194:195], v[234:235]
	v_lshlrev_b32_e32 v232, 16, v169
	v_and_b32_e32 v233, s62, v169
	v_lshlrev_b32_e32 v236, 16, v177
	v_and_b32_e32 v237, s62, v177
	v_pk_fma_f32 v[100:101], v[100:101], v[232:233], v[236:237]
	v_cvt_pk_bf16_f32 v102, v102, v103
	v_cvt_pk_bf16_f32 v103, v104, v105
	v_cvt_pk_bf16_f32 v104, v98, v99
	v_cvt_pk_bf16_f32 v105, v100, v101
	s_add_u32 s28, s10, 0xd8000
	s_addc_u32 s29, s11, 0
	s_add_u32 s30, s8, 0x48000
	s_addc_u32 s31, s9, 0
	global_load_dwordx4 v[162:165], v138, s[28:29]
	global_load_dwordx4 v[170:173], v139, s[30:31]
	global_load_dwordx4 v[166:169], v138, s[28:29] offset:256
	global_load_dwordx4 v[174:177], v139, s[30:31] offset:256
	s_add_u32 s42, s8, 0x8000
	s_addc_u32 s43, s9, 0
	global_store_dwordx4 v139, v[110:113], s[42:43]
	global_store_dwordx4 v139, v[102:105], s[42:43] offset:256
	s_waitcnt vmcnt(18)
	v_lshlrev_b32_e32 v194, 16, v178
	v_and_b32_e32 v195, s62, v178
	v_lshlrev_b32_e32 v234, 16, v190
	v_and_b32_e32 v235, s62, v190
	v_pk_fma_f32 v[94:95], v[94:95], v[194:195], v[234:235]
	v_lshlrev_b32_e32 v232, 16, v179
	v_and_b32_e32 v233, s62, v179
	v_lshlrev_b32_e32 v236, 16, v191
	v_and_b32_e32 v237, s62, v191
	v_pk_fma_f32 v[96:97], v[96:97], v[232:233], v[236:237]
	v_lshlrev_b32_e32 v194, 16, v180
	v_and_b32_e32 v195, s62, v180
	v_lshlrev_b32_e32 v234, 16, v192
	v_and_b32_e32 v235, s62, v192
	v_pk_fma_f32 v[90:91], v[90:91], v[194:195], v[234:235]
	v_lshlrev_b32_e32 v232, 16, v181
	v_and_b32_e32 v233, s62, v181
	v_lshlrev_b32_e32 v236, 16, v193
	v_and_b32_e32 v237, s62, v193
	v_pk_fma_f32 v[92:93], v[92:93], v[232:233], v[236:237]
	v_cvt_pk_bf16_f32 v94, v94, v95
	v_cvt_pk_bf16_f32 v95, v96, v97
	v_cvt_pk_bf16_f32 v96, v90, v91
	v_cvt_pk_bf16_f32 v97, v92, v93
	s_waitcnt vmcnt(16)
	v_lshlrev_b32_e32 v194, 16, v186
	v_and_b32_e32 v195, s62, v186
	v_lshlrev_b32_e32 v234, 16, v212
	v_and_b32_e32 v235, s62, v212
	v_pk_fma_f32 v[86:87], v[86:87], v[194:195], v[234:235]
	v_lshlrev_b32_e32 v232, 16, v187
	v_and_b32_e32 v233, s62, v187
	v_lshlrev_b32_e32 v236, 16, v213
	v_and_b32_e32 v237, s62, v213
	v_pk_fma_f32 v[88:89], v[88:89], v[232:233], v[236:237]
	v_lshlrev_b32_e32 v194, 16, v188
	v_and_b32_e32 v195, s62, v188
	v_lshlrev_b32_e32 v234, 16, v214
	v_and_b32_e32 v235, s62, v214
	v_pk_fma_f32 v[82:83], v[82:83], v[194:195], v[234:235]
	v_lshlrev_b32_e32 v232, 16, v189
	v_and_b32_e32 v233, s62, v189
	v_lshlrev_b32_e32 v236, 16, v215
	v_and_b32_e32 v237, s62, v215
	v_pk_fma_f32 v[84:85], v[84:85], v[232:233], v[236:237]
	v_cvt_pk_bf16_f32 v86, v86, v87
	v_cvt_pk_bf16_f32 v87, v88, v89
	v_cvt_pk_bf16_f32 v88, v82, v83
	v_cvt_pk_bf16_f32 v89, v84, v85
	s_add_u32 s28, s10, 0xf0000
	s_addc_u32 s29, s11, 0
	s_add_u32 s30, s8, 0x50000
	s_addc_u32 s31, s9, 0
	global_load_dwordx4 v[178:181], v138, s[28:29]
	global_load_dwordx4 v[190:193], v139, s[30:31]
	global_load_dwordx4 v[186:189], v138, s[28:29] offset:256
	global_load_dwordx4 v[212:215], v139, s[30:31] offset:256
	s_add_u32 s42, s8, 0x10000
	s_addc_u32 s43, s9, 0
	global_store_dwordx4 v139, v[94:97], s[42:43]
	global_store_dwordx4 v139, v[86:89], s[42:43] offset:256
	s_waitcnt vmcnt(20)
	v_lshlrev_b32_e32 v194, 16, v216
	v_and_b32_e32 v195, s62, v216
	v_lshlrev_b32_e32 v234, 16, v224
	v_and_b32_e32 v235, s62, v224
	v_pk_fma_f32 v[78:79], v[78:79], v[194:195], v[234:235]
	v_lshlrev_b32_e32 v232, 16, v217
	v_and_b32_e32 v233, s62, v217
	v_lshlrev_b32_e32 v236, 16, v225
	v_and_b32_e32 v237, s62, v225
	v_pk_fma_f32 v[80:81], v[80:81], v[232:233], v[236:237]
	v_lshlrev_b32_e32 v194, 16, v218
	v_and_b32_e32 v195, s62, v218
	v_lshlrev_b32_e32 v234, 16, v226
	v_and_b32_e32 v235, s62, v226
	v_pk_fma_f32 v[74:75], v[74:75], v[194:195], v[234:235]
	v_lshlrev_b32_e32 v232, 16, v219
	v_and_b32_e32 v233, s62, v219
	v_lshlrev_b32_e32 v236, 16, v227
	v_and_b32_e32 v237, s62, v227
	v_pk_fma_f32 v[76:77], v[76:77], v[232:233], v[236:237]
	v_cvt_pk_bf16_f32 v78, v78, v79
	v_cvt_pk_bf16_f32 v79, v80, v81
	v_cvt_pk_bf16_f32 v80, v74, v75
	v_cvt_pk_bf16_f32 v81, v76, v77
	s_waitcnt vmcnt(18)
	v_lshlrev_b32_e32 v194, 16, v220
	v_and_b32_e32 v195, s62, v220
	v_lshlrev_b32_e32 v234, 16, v228
	v_and_b32_e32 v235, s62, v228
	v_pk_fma_f32 v[70:71], v[70:71], v[194:195], v[234:235]
	v_lshlrev_b32_e32 v232, 16, v221
	v_and_b32_e32 v233, s62, v221
	v_lshlrev_b32_e32 v236, 16, v229
	v_and_b32_e32 v237, s62, v229
	v_pk_fma_f32 v[72:73], v[72:73], v[232:233], v[236:237]
	v_lshlrev_b32_e32 v194, 16, v222
	v_and_b32_e32 v195, s62, v222
	v_lshlrev_b32_e32 v234, 16, v230
	v_and_b32_e32 v235, s62, v230
	v_pk_fma_f32 v[66:67], v[66:67], v[194:195], v[234:235]
	v_lshlrev_b32_e32 v232, 16, v223
	v_and_b32_e32 v233, s62, v223
	v_lshlrev_b32_e32 v236, 16, v231
	v_and_b32_e32 v237, s62, v231
	v_pk_fma_f32 v[68:69], v[68:69], v[232:233], v[236:237]
	v_cvt_pk_bf16_f32 v70, v70, v71
	v_cvt_pk_bf16_f32 v71, v72, v73
	v_cvt_pk_bf16_f32 v72, v66, v67
	v_cvt_pk_bf16_f32 v73, v68, v69
	s_add_u32 s28, s10, 0x108000
	s_addc_u32 s29, s11, 0
	s_add_u32 s30, s8, 0x58000
	s_addc_u32 s31, s9, 0
	global_load_dwordx4 v[216:219], v138, s[28:29]
	global_load_dwordx4 v[224:227], v139, s[30:31]
	global_load_dwordx4 v[220:223], v138, s[28:29] offset:256
	global_load_dwordx4 v[228:231], v139, s[30:31] offset:256
	s_add_u32 s42, s8, 0x18000
	s_addc_u32 s43, s9, 0
	global_store_dwordx4 v139, v[78:81], s[42:43]
	global_store_dwordx4 v139, v[70:73], s[42:43] offset:256
	s_waitcnt vmcnt(22)
	v_lshlrev_b32_e32 v194, 16, v130
	v_and_b32_e32 v195, s62, v130
	v_lshlrev_b32_e32 v234, 16, v150
	v_and_b32_e32 v235, s62, v150
	v_pk_fma_f32 v[62:63], v[62:63], v[194:195], v[234:235]
	v_lshlrev_b32_e32 v232, 16, v131
	v_and_b32_e32 v233, s62, v131
	v_lshlrev_b32_e32 v236, 16, v151
	v_and_b32_e32 v237, s62, v151
	v_pk_fma_f32 v[64:65], v[64:65], v[232:233], v[236:237]
	v_lshlrev_b32_e32 v194, 16, v132
	v_and_b32_e32 v195, s62, v132
	v_lshlrev_b32_e32 v234, 16, v152
	v_and_b32_e32 v235, s62, v152
	v_pk_fma_f32 v[58:59], v[58:59], v[194:195], v[234:235]
	v_lshlrev_b32_e32 v232, 16, v133
	v_and_b32_e32 v233, s62, v133
	v_lshlrev_b32_e32 v236, 16, v153
	v_and_b32_e32 v237, s62, v153
	v_pk_fma_f32 v[60:61], v[60:61], v[232:233], v[236:237]
	v_cvt_pk_bf16_f32 v62, v62, v63
	v_cvt_pk_bf16_f32 v63, v64, v65
	v_cvt_pk_bf16_f32 v64, v58, v59
	v_cvt_pk_bf16_f32 v65, v60, v61
	s_waitcnt vmcnt(20)
	v_lshlrev_b32_e32 v194, 16, v134
	v_and_b32_e32 v195, s62, v134
	v_lshlrev_b32_e32 v234, 16, v154
	v_and_b32_e32 v235, s62, v154
	v_pk_fma_f32 v[54:55], v[54:55], v[194:195], v[234:235]
	v_lshlrev_b32_e32 v232, 16, v135
	v_and_b32_e32 v233, s62, v135
	v_lshlrev_b32_e32 v236, 16, v155
	v_and_b32_e32 v237, s62, v155
	v_pk_fma_f32 v[56:57], v[56:57], v[232:233], v[236:237]
	v_lshlrev_b32_e32 v194, 16, v136
	v_and_b32_e32 v195, s62, v136
	v_lshlrev_b32_e32 v234, 16, v156
	v_and_b32_e32 v235, s62, v156
	v_pk_fma_f32 v[50:51], v[50:51], v[194:195], v[234:235]
	v_lshlrev_b32_e32 v232, 16, v137
	v_and_b32_e32 v233, s62, v137
	v_lshlrev_b32_e32 v236, 16, v157
	v_and_b32_e32 v237, s62, v157
	v_pk_fma_f32 v[52:53], v[52:53], v[232:233], v[236:237]
	v_cvt_pk_bf16_f32 v54, v54, v55
	v_cvt_pk_bf16_f32 v55, v56, v57
	v_cvt_pk_bf16_f32 v56, v50, v51
	v_cvt_pk_bf16_f32 v57, v52, v53
	s_add_u32 s42, s8, 0x40000
	s_addc_u32 s43, s9, 0
	global_store_dwordx4 v139, v[62:65], s[42:43]
	global_store_dwordx4 v139, v[54:57], s[42:43] offset:256
	s_waitcnt vmcnt(18)
	v_lshlrev_b32_e32 v194, 16, v162
	v_and_b32_e32 v195, s62, v162
	v_lshlrev_b32_e32 v234, 16, v170
	v_and_b32_e32 v235, s62, v170
	v_pk_fma_f32 v[46:47], v[46:47], v[194:195], v[234:235]
	v_lshlrev_b32_e32 v232, 16, v163
	v_and_b32_e32 v233, s62, v163
	v_lshlrev_b32_e32 v236, 16, v171
	v_and_b32_e32 v237, s62, v171
	v_pk_fma_f32 v[48:49], v[48:49], v[232:233], v[236:237]
	v_lshlrev_b32_e32 v194, 16, v164
	v_and_b32_e32 v195, s62, v164
	v_lshlrev_b32_e32 v234, 16, v172
	v_and_b32_e32 v235, s62, v172
	v_pk_fma_f32 v[42:43], v[42:43], v[194:195], v[234:235]
	v_lshlrev_b32_e32 v232, 16, v165
	v_and_b32_e32 v233, s62, v165
	v_lshlrev_b32_e32 v236, 16, v173
	v_and_b32_e32 v237, s62, v173
	v_pk_fma_f32 v[44:45], v[44:45], v[232:233], v[236:237]
	v_cvt_pk_bf16_f32 v46, v46, v47
	v_cvt_pk_bf16_f32 v47, v48, v49
	v_cvt_pk_bf16_f32 v48, v42, v43
	v_cvt_pk_bf16_f32 v49, v44, v45
	s_waitcnt vmcnt(16)
	v_lshlrev_b32_e32 v194, 16, v166
	v_and_b32_e32 v195, s62, v166
	v_lshlrev_b32_e32 v234, 16, v174
	v_and_b32_e32 v235, s62, v174
	v_pk_fma_f32 v[38:39], v[38:39], v[194:195], v[234:235]
	v_lshlrev_b32_e32 v232, 16, v167
	v_and_b32_e32 v233, s62, v167
	v_lshlrev_b32_e32 v236, 16, v175
	v_and_b32_e32 v237, s62, v175
	v_pk_fma_f32 v[40:41], v[40:41], v[232:233], v[236:237]
	v_lshlrev_b32_e32 v194, 16, v168
	v_and_b32_e32 v195, s62, v168
	v_lshlrev_b32_e32 v234, 16, v176
	v_and_b32_e32 v235, s62, v176
	v_pk_fma_f32 v[34:35], v[34:35], v[194:195], v[234:235]
	v_lshlrev_b32_e32 v232, 16, v169
	v_and_b32_e32 v233, s62, v169
	v_lshlrev_b32_e32 v236, 16, v177
	v_and_b32_e32 v237, s62, v177
	v_pk_fma_f32 v[36:37], v[36:37], v[232:233], v[236:237]
	v_cvt_pk_bf16_f32 v38, v38, v39
	v_cvt_pk_bf16_f32 v39, v40, v41
	v_cvt_pk_bf16_f32 v40, v34, v35
	v_cvt_pk_bf16_f32 v41, v36, v37
	s_add_u32 s42, s8, 0x48000
	s_addc_u32 s43, s9, 0
	global_store_dwordx4 v139, v[46:49], s[42:43]
	global_store_dwordx4 v139, v[38:41], s[42:43] offset:256
	s_waitcnt vmcnt(14)
	v_lshlrev_b32_e32 v194, 16, v178
	v_and_b32_e32 v195, s62, v178
	v_lshlrev_b32_e32 v234, 16, v190
	v_and_b32_e32 v235, s62, v190
	v_pk_fma_f32 v[30:31], v[30:31], v[194:195], v[234:235]
	v_lshlrev_b32_e32 v232, 16, v179
	v_and_b32_e32 v233, s62, v179
	v_lshlrev_b32_e32 v236, 16, v191
	v_and_b32_e32 v237, s62, v191
	v_pk_fma_f32 v[32:33], v[32:33], v[232:233], v[236:237]
	v_lshlrev_b32_e32 v194, 16, v180
	v_and_b32_e32 v195, s62, v180
	v_lshlrev_b32_e32 v234, 16, v192
	v_and_b32_e32 v235, s62, v192
	v_pk_fma_f32 v[26:27], v[26:27], v[194:195], v[234:235]
	v_lshlrev_b32_e32 v232, 16, v181
	v_and_b32_e32 v233, s62, v181
	v_lshlrev_b32_e32 v236, 16, v193
	v_and_b32_e32 v237, s62, v193
	v_pk_fma_f32 v[28:29], v[28:29], v[232:233], v[236:237]
	v_cvt_pk_bf16_f32 v30, v30, v31
	v_cvt_pk_bf16_f32 v31, v32, v33
	v_cvt_pk_bf16_f32 v32, v26, v27
	v_cvt_pk_bf16_f32 v33, v28, v29
	s_waitcnt vmcnt(12)
	v_lshlrev_b32_e32 v194, 16, v186
	v_and_b32_e32 v195, s62, v186
	v_lshlrev_b32_e32 v234, 16, v212
	v_and_b32_e32 v235, s62, v212
	v_pk_fma_f32 v[22:23], v[22:23], v[194:195], v[234:235]
	v_lshlrev_b32_e32 v232, 16, v187
	v_and_b32_e32 v233, s62, v187
	v_lshlrev_b32_e32 v236, 16, v213
	v_and_b32_e32 v237, s62, v213
	v_pk_fma_f32 v[24:25], v[24:25], v[232:233], v[236:237]
	v_lshlrev_b32_e32 v194, 16, v188
	v_and_b32_e32 v195, s62, v188
	v_lshlrev_b32_e32 v234, 16, v214
	v_and_b32_e32 v235, s62, v214
	v_pk_fma_f32 v[18:19], v[18:19], v[194:195], v[234:235]
	v_lshlrev_b32_e32 v232, 16, v189
	v_and_b32_e32 v233, s62, v189
	v_lshlrev_b32_e32 v236, 16, v215
	v_and_b32_e32 v237, s62, v215
	v_pk_fma_f32 v[20:21], v[20:21], v[232:233], v[236:237]
	v_cvt_pk_bf16_f32 v22, v22, v23
	v_cvt_pk_bf16_f32 v23, v24, v25
	v_cvt_pk_bf16_f32 v24, v18, v19
	v_cvt_pk_bf16_f32 v25, v20, v21
	s_add_u32 s42, s8, 0x50000
	s_addc_u32 s43, s9, 0
	global_store_dwordx4 v139, v[30:33], s[42:43]
	global_store_dwordx4 v139, v[22:25], s[42:43] offset:256
	s_waitcnt vmcnt(10)
	v_lshlrev_b32_e32 v194, 16, v216
	v_and_b32_e32 v195, s62, v216
	v_lshlrev_b32_e32 v234, 16, v224
	v_and_b32_e32 v235, s62, v224
	v_pk_fma_f32 v[14:15], v[14:15], v[194:195], v[234:235]
	v_lshlrev_b32_e32 v232, 16, v217
	v_and_b32_e32 v233, s62, v217
	v_lshlrev_b32_e32 v236, 16, v225
	v_and_b32_e32 v237, s62, v225
	v_pk_fma_f32 v[16:17], v[16:17], v[232:233], v[236:237]
	v_lshlrev_b32_e32 v194, 16, v218
	v_and_b32_e32 v195, s62, v218
	v_lshlrev_b32_e32 v234, 16, v226
	v_and_b32_e32 v235, s62, v226
	v_pk_fma_f32 v[10:11], v[10:11], v[194:195], v[234:235]
	v_lshlrev_b32_e32 v232, 16, v219
	v_and_b32_e32 v233, s62, v219
	v_lshlrev_b32_e32 v236, 16, v227
	v_and_b32_e32 v237, s62, v227
	v_pk_fma_f32 v[12:13], v[12:13], v[232:233], v[236:237]
	v_cvt_pk_bf16_f32 v14, v14, v15
	v_cvt_pk_bf16_f32 v15, v16, v17
	v_cvt_pk_bf16_f32 v16, v10, v11
	v_cvt_pk_bf16_f32 v17, v12, v13
	s_waitcnt vmcnt(8)
	v_lshlrev_b32_e32 v194, 16, v220
	v_and_b32_e32 v195, s62, v220
	v_lshlrev_b32_e32 v234, 16, v228
	v_and_b32_e32 v235, s62, v228
	v_pk_fma_f32 v[6:7], v[6:7], v[194:195], v[234:235]
	v_lshlrev_b32_e32 v232, 16, v221
	v_and_b32_e32 v233, s62, v221
	v_lshlrev_b32_e32 v236, 16, v229
	v_and_b32_e32 v237, s62, v229
	v_pk_fma_f32 v[8:9], v[8:9], v[232:233], v[236:237]
	v_lshlrev_b32_e32 v194, 16, v222
	v_and_b32_e32 v195, s62, v222
	v_lshlrev_b32_e32 v234, 16, v230
	v_and_b32_e32 v235, s62, v230
	v_pk_fma_f32 v[2:3], v[2:3], v[194:195], v[234:235]
	v_lshlrev_b32_e32 v232, 16, v223
	v_and_b32_e32 v233, s62, v223
	v_lshlrev_b32_e32 v236, 16, v231
	v_and_b32_e32 v237, s62, v231
	v_pk_fma_f32 v[4:5], v[4:5], v[232:233], v[236:237]
	v_cvt_pk_bf16_f32 v6, v6, v7
	v_cvt_pk_bf16_f32 v7, v8, v9
	v_cvt_pk_bf16_f32 v8, v2, v3
	v_cvt_pk_bf16_f32 v9, v4, v5
	s_add_u32 s42, s8, 0x58000
	s_addc_u32 s43, s9, 0
	global_store_dwordx4 v139, v[14:17], s[42:43]
	global_store_dwordx4 v139, v[6:9], s[42:43] offset:256
	s_branch .Lp6_epi_done
.Lp6_first:
	v_mov_b32_e32 v236, 0
	v_mov_b32_e32 v237, 0
	s_add_u32 s28, s10, 0x0
	s_addc_u32 s29, s11, 0
	global_load_dwordx4 v[130:133], v138, s[28:29]
	global_load_dwordx4 v[134:137], v138, s[28:29] offset:256
	s_add_u32 s28, s10, 0x18000
	s_addc_u32 s29, s11, 0
	global_load_dwordx4 v[150:153], v138, s[28:29]
	global_load_dwordx4 v[154:157], v138, s[28:29] offset:256
	s_add_u32 s28, s10, 0x30000
	s_addc_u32 s29, s11, 0
	global_load_dwordx4 v[162:165], v138, s[28:29]
	global_load_dwordx4 v[166:169], v138, s[28:29] offset:256
	s_add_u32 s28, s10, 0x48000
	s_addc_u32 s29, s11, 0
	global_load_dwordx4 v[170:173], v138, s[28:29]
	global_load_dwordx4 v[174:177], v138, s[28:29] offset:256
	s_add_u32 s28, s10, 0xc0000
	s_addc_u32 s29, s11, 0
	global_load_dwordx4 v[178:181], v138, s[28:29]
	global_load_dwordx4 v[186:189], v138, s[28:29] offset:256
	s_add_u32 s28, s10, 0xd8000
	s_addc_u32 s29, s11, 0
	global_load_dwordx4 v[190:193], v138, s[28:29]
	global_load_dwordx4 v[212:215], v138, s[28:29] offset:256
	s_add_u32 s28, s10, 0xf0000
	s_addc_u32 s29, s11, 0
	global_load_dwordx4 v[216:219], v138, s[28:29]
	global_load_dwordx4 v[220:223], v138, s[28:29] offset:256
	s_add_u32 s28, s10, 0x108000
	s_addc_u32 s29, s11, 0
	global_load_dwordx4 v[224:227], v138, s[28:29]
	global_load_dwordx4 v[228:231], v138, s[28:29] offset:256
	ds_bpermute_b32 v2, v235, v2
	ds_bpermute_b32 v3, v235, v3
	ds_bpermute_b32 v4, v235, v4
	ds_bpermute_b32 v5, v235, v5
	ds_bpermute_b32 v6, v235, v6
	ds_bpermute_b32 v7, v235, v7
	ds_bpermute_b32 v8, v235, v8
	s_waitcnt lgkmcnt(7)
	ds_bpermute_b32 v9, v235, v9
	ds_bpermute_b32 v10, v235, v10
	ds_bpermute_b32 v11, v235, v11
	ds_bpermute_b32 v12, v235, v12
	ds_bpermute_b32 v13, v235, v13
	ds_bpermute_b32 v14, v235, v14
	ds_bpermute_b32 v15, v235, v15
	s_waitcnt lgkmcnt(7)
	ds_bpermute_b32 v16, v235, v16
	ds_bpermute_b32 v17, v235, v17
	ds_bpermute_b32 v18, v235, v18
	ds_bpermute_b32 v19, v235, v19
	ds_bpermute_b32 v20, v235, v20
	ds_bpermute_b32 v21, v235, v21
	ds_bpermute_b32 v22, v235, v22
	s_waitcnt lgkmcnt(7)
	ds_bpermute_b32 v23, v235, v23
	ds_bpermute_b32 v24, v235, v24
	ds_bpermute_b32 v25, v235, v25
	ds_bpermute_b32 v26, v235, v26
	ds_bpermute_b32 v27, v235, v27
	ds_bpermute_b32 v28, v235, v28
	ds_bpermute_b32 v29, v235, v29
	s_waitcnt lgkmcnt(7)
	ds_bpermute_b32 v30, v235, v30
	ds_bpermute_b32 v31, v235, v31
	ds_bpermute_b32 v32, v235, v32
	ds_bpermute_b32 v33, v235, v33
	ds_bpermute_b32 v34, v235, v34
	ds_bpermute_b32 v35, v235, v35
	ds_bpermute_b32 v36, v235, v36
	s_waitcnt lgkmcnt(7)
	ds_bpermute_b32 v37, v235, v37
	ds_bpermute_b32 v38, v235, v38
	ds_bpermute_b32 v39, v235, v39
	ds_bpermute_b32 v40, v235, v40
	ds_bpermute_b32 v41, v235, v41
	ds_bpermute_b32 v42, v235, v42
	ds_bpermute_b32 v43, v235, v43
	s_waitcnt lgkmcnt(7)
	ds_bpermute_b32 v44, v235, v44
	ds_bpermute_b32 v45, v235, v45
	ds_bpermute_b32 v46, v235, v46
	ds_bpermute_b32 v47, v235, v47
	ds_bpermute_b32 v48, v235, v48
	ds_bpermute_b32 v49, v235, v49
	ds_bpermute_b32 v50, v235, v50
	s_waitcnt lgkmcnt(7)
	ds_bpermute_b32 v51, v235, v51
	ds_bpermute_b32 v52, v235, v52
	ds_bpermute_b32 v53, v235, v53
	ds_bpermute_b32 v54, v235, v54
	ds_bpermute_b32 v55, v235, v55
	ds_bpermute_b32 v56, v235, v56
	ds_bpermute_b32 v57, v235, v57
	s_waitcnt lgkmcnt(7)
	ds_bpermute_b32 v58, v235, v58
	ds_bpermute_b32 v59, v235, v59
	ds_bpermute_b32 v60, v235, v60
	ds_bpermute_b32 v61, v235, v61
	ds_bpermute_b32 v62, v235, v62
	ds_bpermute_b32 v63, v235, v63
	ds_bpermute_b32 v64, v235, v64
	s_waitcnt lgkmcnt(7)
	ds_bpermute_b32 v65, v235, v65
	ds_bpermute_b32 v66, v235, v66
	ds_bpermute_b32 v67, v235, v67
	ds_bpermute_b32 v68, v235, v68
	ds_bpermute_b32 v69, v235, v69
	ds_bpermute_b32 v70, v235, v70
	ds_bpermute_b32 v71, v235, v71
	s_waitcnt lgkmcnt(7)
	ds_bpermute_b32 v72, v235, v72
	ds_bpermute_b32 v73, v235, v73
	ds_bpermute_b32 v74, v235, v74
	ds_bpermute_b32 v75, v235, v75
	ds_bpermute_b32 v76, v235, v76
	ds_bpermute_b32 v77, v235, v77
	ds_bpermute_b32 v78, v235, v78
	s_waitcnt lgkmcnt(7)
	ds_bpermute_b32 v79, v235, v79
	ds_bpermute_b32 v80, v235, v80
	ds_bpermute_b32 v81, v235, v81
	ds_bpermute_b32 v82, v235, v82
	ds_bpermute_b32 v83, v235, v83
	ds_bpermute_b32 v84, v235, v84
	ds_bpermute_b32 v85, v235, v85
	s_waitcnt lgkmcnt(7)
	ds_bpermute_b32 v86, v235, v86
	ds_bpermute_b32 v87, v235, v87
	ds_bpermute_b32 v88, v235, v88
	ds_bpermute_b32 v89, v235, v89
	ds_bpermute_b32 v90, v235, v90
	ds_bpermute_b32 v91, v235, v91
	ds_bpermute_b32 v92, v235, v92
	s_waitcnt lgkmcnt(7)
	ds_bpermute_b32 v93, v235, v93
	ds_bpermute_b32 v94, v235, v94
	ds_bpermute_b32 v95, v235, v95
	ds_bpermute_b32 v96, v235, v96
	ds_bpermute_b32 v97, v235, v97
	ds_bpermute_b32 v98, v235, v98
	ds_bpermute_b32 v99, v235, v99
	s_waitcnt lgkmcnt(7)
	ds_bpermute_b32 v100, v235, v100
	ds_bpermute_b32 v101, v235, v101
	ds_bpermute_b32 v102, v235, v102
	ds_bpermute_b32 v103, v235, v103
	ds_bpermute_b32 v104, v235, v104
	ds_bpermute_b32 v105, v235, v105
	ds_bpermute_b32 v106, v235, v106
	s_waitcnt lgkmcnt(7)
	ds_bpermute_b32 v107, v235, v107
	ds_bpermute_b32 v108, v235, v108
	ds_bpermute_b32 v109, v235, v109
	ds_bpermute_b32 v110, v235, v110
	ds_bpermute_b32 v111, v235, v111
	ds_bpermute_b32 v112, v235, v112
	ds_bpermute_b32 v113, v235, v113
	s_waitcnt lgkmcnt(7)
	ds_bpermute_b32 v114, v235, v114
	ds_bpermute_b32 v115, v235, v115
	ds_bpermute_b32 v116, v235, v116
	ds_bpermute_b32 v117, v235, v117
	ds_bpermute_b32 v118, v235, v118
	ds_bpermute_b32 v119, v235, v119
	ds_bpermute_b32 v120, v235, v120
	s_waitcnt lgkmcnt(7)
	ds_bpermute_b32 v121, v235, v121
	ds_bpermute_b32 v122, v235, v122
	ds_bpermute_b32 v123, v235, v123
	ds_bpermute_b32 v124, v235, v124
	ds_bpermute_b32 v125, v235, v125
	ds_bpermute_b32 v126, v235, v126
	ds_bpermute_b32 v127, v235, v127
	s_waitcnt lgkmcnt(7)
	ds_bpermute_b32 v128, v235, v128
	ds_bpermute_b32 v129, v235, v129
	s_waitcnt lgkmcnt(0)
	s_waitcnt vmcnt(15)
	v_lshlrev_b32_e32 v194, 16, v130
	v_and_b32_e32 v195, s62, v130
	v_pk_fma_f32 v[126:127], v[126:127], v[194:195], v[236:237]
	v_lshlrev_b32_e32 v232, 16, v131
	v_and_b32_e32 v233, s62, v131
	v_pk_fma_f32 v[128:129], v[128:129], v[232:233], v[236:237]
	v_lshlrev_b32_e32 v194, 16, v132
	v_and_b32_e32 v195, s62, v132
	v_pk_fma_f32 v[122:123], v[122:123], v[194:195], v[236:237]
	v_lshlrev_b32_e32 v232, 16, v133
	v_and_b32_e32 v233, s62, v133
	v_pk_fma_f32 v[124:125], v[124:125], v[232:233], v[236:237]
	v_cvt_pk_bf16_f32 v126, v126, v127
	v_cvt_pk_bf16_f32 v127, v128, v129
	v_cvt_pk_bf16_f32 v128, v122, v123
	v_cvt_pk_bf16_f32 v129, v124, v125
	s_waitcnt vmcnt(14)
	v_lshlrev_b32_e32 v194, 16, v134
	v_and_b32_e32 v195, s62, v134
	v_pk_fma_f32 v[118:119], v[118:119], v[194:195], v[236:237]
	v_lshlrev_b32_e32 v232, 16, v135
	v_and_b32_e32 v233, s62, v135
	v_pk_fma_f32 v[120:121], v[120:121], v[232:233], v[236:237]
	v_lshlrev_b32_e32 v194, 16, v136
	v_and_b32_e32 v195, s62, v136
	v_pk_fma_f32 v[114:115], v[114:115], v[194:195], v[236:237]
	v_lshlrev_b32_e32 v232, 16, v137
	v_and_b32_e32 v233, s62, v137
	v_pk_fma_f32 v[116:117], v[116:117], v[232:233], v[236:237]
	v_cvt_pk_bf16_f32 v118, v118, v119
	v_cvt_pk_bf16_f32 v119, v120, v121
	v_cvt_pk_bf16_f32 v120, v114, v115
	v_cvt_pk_bf16_f32 v121, v116, v117
	s_add_u32 s42, s8, 0x0
	s_addc_u32 s43, s9, 0
	global_store_dwordx4 v139, v[126:129], s[42:43]
	global_store_dwordx4 v139, v[118:121], s[42:43] offset:256
	s_waitcnt vmcnt(15)
	v_lshlrev_b32_e32 v194, 16, v150
	v_and_b32_e32 v195, s62, v150
	v_pk_fma_f32 v[110:111], v[110:111], v[194:195], v[236:237]
	v_lshlrev_b32_e32 v232, 16, v151
	v_and_b32_e32 v233, s62, v151
	v_pk_fma_f32 v[112:113], v[112:113], v[232:233], v[236:237]
	v_lshlrev_b32_e32 v194, 16, v152
	v_and_b32_e32 v195, s62, v152
	v_pk_fma_f32 v[106:107], v[106:107], v[194:195], v[236:237]
	v_lshlrev_b32_e32 v232, 16, v153
	v_and_b32_e32 v233, s62, v153
	v_pk_fma_f32 v[108:109], v[108:109], v[232:233], v[236:237]
	v_cvt_pk_bf16_f32 v110, v110, v111
	v_cvt_pk_bf16_f32 v111, v112, v113
	v_cvt_pk_bf16_f32 v112, v106, v107
	v_cvt_pk_bf16_f32 v113, v108, v109
	s_waitcnt vmcnt(14)
	v_lshlrev_b32_e32 v194, 16, v154
	v_and_b32_e32 v195, s62, v154
	v_pk_fma_f32 v[102:103], v[102:103], v[194:195], v[236:237]
	v_lshlrev_b32_e32 v232, 16, v155
	v_and_b32_e32 v233, s62, v155
	v_pk_fma_f32 v[104:105], v[104:105], v[232:233], v[236:237]
	v_lshlrev_b32_e32 v194, 16, v156
	v_and_b32_e32 v195, s62, v156
	v_pk_fma_f32 v[98:99], v[98:99], v[194:195], v[236:237]
	v_lshlrev_b32_e32 v232, 16, v157
	v_and_b32_e32 v233, s62, v157
	v_pk_fma_f32 v[100:101], v[100:101], v[232:233], v[236:237]
	v_cvt_pk_bf16_f32 v102, v102, v103
	v_cvt_pk_bf16_f32 v103, v104, v105
	v_cvt_pk_bf16_f32 v104, v98, v99
	v_cvt_pk_bf16_f32 v105, v100, v101
	s_add_u32 s42, s8, 0x8000
	s_addc_u32 s43, s9, 0
	global_store_dwordx4 v139, v[110:113], s[42:43]
	global_store_dwordx4 v139, v[102:105], s[42:43] offset:256
	s_waitcnt vmcnt(15)
	v_lshlrev_b32_e32 v194, 16, v162
	v_and_b32_e32 v195, s62, v162
	v_pk_fma_f32 v[94:95], v[94:95], v[194:195], v[236:237]
	v_lshlrev_b32_e32 v232, 16, v163
	v_and_b32_e32 v233, s62, v163
	v_pk_fma_f32 v[96:97], v[96:97], v[232:233], v[236:237]
	v_lshlrev_b32_e32 v194, 16, v164
	v_and_b32_e32 v195, s62, v164
	v_pk_fma_f32 v[90:91], v[90:91], v[194:195], v[236:237]
	v_lshlrev_b32_e32 v232, 16, v165
	v_and_b32_e32 v233, s62, v165
	v_pk_fma_f32 v[92:93], v[92:93], v[232:233], v[236:237]
	v_cvt_pk_bf16_f32 v94, v94, v95
	v_cvt_pk_bf16_f32 v95, v96, v97
	v_cvt_pk_bf16_f32 v96, v90, v91
	v_cvt_pk_bf16_f32 v97, v92, v93
	s_waitcnt vmcnt(14)
	v_lshlrev_b32_e32 v194, 16, v166
	v_and_b32_e32 v195, s62, v166
	v_pk_fma_f32 v[86:87], v[86:87], v[194:195], v[236:237]
	v_lshlrev_b32_e32 v232, 16, v167
	v_and_b32_e32 v233, s62, v167
	v_pk_fma_f32 v[88:89], v[88:89], v[232:233], v[236:237]
	v_lshlrev_b32_e32 v194, 16, v168
	v_and_b32_e32 v195, s62, v168
	v_pk_fma_f32 v[82:83], v[82:83], v[194:195], v[236:237]
	v_lshlrev_b32_e32 v232, 16, v169
	v_and_b32_e32 v233, s62, v169
	v_pk_fma_f32 v[84:85], v[84:85], v[232:233], v[236:237]
	v_cvt_pk_bf16_f32 v86, v86, v87
	v_cvt_pk_bf16_f32 v87, v88, v89
	v_cvt_pk_bf16_f32 v88, v82, v83
	v_cvt_pk_bf16_f32 v89, v84, v85
	s_add_u32 s42, s8, 0x10000
	s_addc_u32 s43, s9, 0
	global_store_dwordx4 v139, v[94:97], s[42:43]
	global_store_dwordx4 v139, v[86:89], s[42:43] offset:256
	s_waitcnt vmcnt(15)
	v_lshlrev_b32_e32 v194, 16, v170
	v_and_b32_e32 v195, s62, v170
	v_pk_fma_f32 v[78:79], v[78:79], v[194:195], v[236:237]
	v_lshlrev_b32_e32 v232, 16, v171
	v_and_b32_e32 v233, s62, v171
	v_pk_fma_f32 v[80:81], v[80:81], v[232:233], v[236:237]
	v_lshlrev_b32_e32 v194, 16, v172
	v_and_b32_e32 v195, s62, v172
	v_pk_fma_f32 v[74:75], v[74:75], v[194:195], v[236:237]
	v_lshlrev_b32_e32 v232, 16, v173
	v_and_b32_e32 v233, s62, v173
	v_pk_fma_f32 v[76:77], v[76:77], v[232:233], v[236:237]
	v_cvt_pk_bf16_f32 v78, v78, v79
	v_cvt_pk_bf16_f32 v79, v80, v81
	v_cvt_pk_bf16_f32 v80, v74, v75
	v_cvt_pk_bf16_f32 v81, v76, v77
	s_waitcnt vmcnt(14)
	v_lshlrev_b32_e32 v194, 16, v174
	v_and_b32_e32 v195, s62, v174
	v_pk_fma_f32 v[70:71], v[70:71], v[194:195], v[236:237]
	v_lshlrev_b32_e32 v232, 16, v175
	v_and_b32_e32 v233, s62, v175
	v_pk_fma_f32 v[72:73], v[72:73], v[232:233], v[236:237]
	v_lshlrev_b32_e32 v194, 16, v176
	v_and_b32_e32 v195, s62, v176
	v_pk_fma_f32 v[66:67], v[66:67], v[194:195], v[236:237]
	v_lshlrev_b32_e32 v232, 16, v177
	v_and_b32_e32 v233, s62, v177
	v_pk_fma_f32 v[68:69], v[68:69], v[232:233], v[236:237]
	v_cvt_pk_bf16_f32 v70, v70, v71
	v_cvt_pk_bf16_f32 v71, v72, v73
	v_cvt_pk_bf16_f32 v72, v66, v67
	v_cvt_pk_bf16_f32 v73, v68, v69
	s_add_u32 s42, s8, 0x18000
	s_addc_u32 s43, s9, 0
	global_store_dwordx4 v139, v[78:81], s[42:43]
	global_store_dwordx4 v139, v[70:73], s[42:43] offset:256
	s_waitcnt vmcnt(15)
	v_lshlrev_b32_e32 v194, 16, v178
	v_and_b32_e32 v195, s62, v178
	v_pk_fma_f32 v[62:63], v[62:63], v[194:195], v[236:237]
	v_lshlrev_b32_e32 v232, 16, v179
	v_and_b32_e32 v233, s62, v179
	v_pk_fma_f32 v[64:65], v[64:65], v[232:233], v[236:237]
	v_lshlrev_b32_e32 v194, 16, v180
	v_and_b32_e32 v195, s62, v180
	v_pk_fma_f32 v[58:59], v[58:59], v[194:195], v[236:237]
	v_lshlrev_b32_e32 v232, 16, v181
	v_and_b32_e32 v233, s62, v181
	v_pk_fma_f32 v[60:61], v[60:61], v[232:233], v[236:237]
	v_cvt_pk_bf16_f32 v62, v62, v63
	v_cvt_pk_bf16_f32 v63, v64, v65
	v_cvt_pk_bf16_f32 v64, v58, v59
	v_cvt_pk_bf16_f32 v65, v60, v61
	s_waitcnt vmcnt(14)
	v_lshlrev_b32_e32 v194, 16, v186
	v_and_b32_e32 v195, s62, v186
	v_pk_fma_f32 v[54:55], v[54:55], v[194:195], v[236:237]
	v_lshlrev_b32_e32 v232, 16, v187
	v_and_b32_e32 v233, s62, v187
	v_pk_fma_f32 v[56:57], v[56:57], v[232:233], v[236:237]
	v_lshlrev_b32_e32 v194, 16, v188
	v_and_b32_e32 v195, s62, v188
	v_pk_fma_f32 v[50:51], v[50:51], v[194:195], v[236:237]
	v_lshlrev_b32_e32 v232, 16, v189
	v_and_b32_e32 v233, s62, v189
	v_pk_fma_f32 v[52:53], v[52:53], v[232:233], v[236:237]
	v_cvt_pk_bf16_f32 v54, v54, v55
	v_cvt_pk_bf16_f32 v55, v56, v57
	v_cvt_pk_bf16_f32 v56, v50, v51
	v_cvt_pk_bf16_f32 v57, v52, v53
	s_add_u32 s42, s8, 0x40000
	s_addc_u32 s43, s9, 0
	global_store_dwordx4 v139, v[62:65], s[42:43]
	global_store_dwordx4 v139, v[54:57], s[42:43] offset:256
	s_waitcnt vmcnt(15)
	v_lshlrev_b32_e32 v194, 16, v190
	v_and_b32_e32 v195, s62, v190
	v_pk_fma_f32 v[46:47], v[46:47], v[194:195], v[236:237]
	v_lshlrev_b32_e32 v232, 16, v191
	v_and_b32_e32 v233, s62, v191
	v_pk_fma_f32 v[48:49], v[48:49], v[232:233], v[236:237]
	v_lshlrev_b32_e32 v194, 16, v192
	v_and_b32_e32 v195, s62, v192
	v_pk_fma_f32 v[42:43], v[42:43], v[194:195], v[236:237]
	v_lshlrev_b32_e32 v232, 16, v193
	v_and_b32_e32 v233, s62, v193
	v_pk_fma_f32 v[44:45], v[44:45], v[232:233], v[236:237]
	v_cvt_pk_bf16_f32 v46, v46, v47
	v_cvt_pk_bf16_f32 v47, v48, v49
	v_cvt_pk_bf16_f32 v48, v42, v43
	v_cvt_pk_bf16_f32 v49, v44, v45
	s_waitcnt vmcnt(14)
	v_lshlrev_b32_e32 v194, 16, v212
	v_and_b32_e32 v195, s62, v212
	v_pk_fma_f32 v[38:39], v[38:39], v[194:195], v[236:237]
	v_lshlrev_b32_e32 v232, 16, v213
	v_and_b32_e32 v233, s62, v213
	v_pk_fma_f32 v[40:41], v[40:41], v[232:233], v[236:237]
	v_lshlrev_b32_e32 v194, 16, v214
	v_and_b32_e32 v195, s62, v214
	v_pk_fma_f32 v[34:35], v[34:35], v[194:195], v[236:237]
	v_lshlrev_b32_e32 v232, 16, v215
	v_and_b32_e32 v233, s62, v215
	v_pk_fma_f32 v[36:37], v[36:37], v[232:233], v[236:237]
	v_cvt_pk_bf16_f32 v38, v38, v39
	v_cvt_pk_bf16_f32 v39, v40, v41
	v_cvt_pk_bf16_f32 v40, v34, v35
	v_cvt_pk_bf16_f32 v41, v36, v37
	s_add_u32 s42, s8, 0x48000
	s_addc_u32 s43, s9, 0
	global_store_dwordx4 v139, v[46:49], s[42:43]
	global_store_dwordx4 v139, v[38:41], s[42:43] offset:256
	s_waitcnt vmcnt(15)
	v_lshlrev_b32_e32 v194, 16, v216
	v_and_b32_e32 v195, s62, v216
	v_pk_fma_f32 v[30:31], v[30:31], v[194:195], v[236:237]
	v_lshlrev_b32_e32 v232, 16, v217
	v_and_b32_e32 v233, s62, v217
	v_pk_fma_f32 v[32:33], v[32:33], v[232:233], v[236:237]
	v_lshlrev_b32_e32 v194, 16, v218
	v_and_b32_e32 v195, s62, v218
	v_pk_fma_f32 v[26:27], v[26:27], v[194:195], v[236:237]
	v_lshlrev_b32_e32 v232, 16, v219
	v_and_b32_e32 v233, s62, v219
	v_pk_fma_f32 v[28:29], v[28:29], v[232:233], v[236:237]
	v_cvt_pk_bf16_f32 v30, v30, v31
	v_cvt_pk_bf16_f32 v31, v32, v33
	v_cvt_pk_bf16_f32 v32, v26, v27
	v_cvt_pk_bf16_f32 v33, v28, v29
	s_waitcnt vmcnt(14)
	v_lshlrev_b32_e32 v194, 16, v220
	v_and_b32_e32 v195, s62, v220
	v_pk_fma_f32 v[22:23], v[22:23], v[194:195], v[236:237]
	v_lshlrev_b32_e32 v232, 16, v221
	v_and_b32_e32 v233, s62, v221
	v_pk_fma_f32 v[24:25], v[24:25], v[232:233], v[236:237]
	v_lshlrev_b32_e32 v194, 16, v222
	v_and_b32_e32 v195, s62, v222
	v_pk_fma_f32 v[18:19], v[18:19], v[194:195], v[236:237]
	v_lshlrev_b32_e32 v232, 16, v223
	v_and_b32_e32 v233, s62, v223
	v_pk_fma_f32 v[20:21], v[20:21], v[232:233], v[236:237]
	v_cvt_pk_bf16_f32 v22, v22, v23
	v_cvt_pk_bf16_f32 v23, v24, v25
	v_cvt_pk_bf16_f32 v24, v18, v19
	v_cvt_pk_bf16_f32 v25, v20, v21
	s_add_u32 s42, s8, 0x50000
	s_addc_u32 s43, s9, 0
	global_store_dwordx4 v139, v[30:33], s[42:43]
	global_store_dwordx4 v139, v[22:25], s[42:43] offset:256
	s_waitcnt vmcnt(15)
	v_lshlrev_b32_e32 v194, 16, v224
	v_and_b32_e32 v195, s62, v224
	v_pk_fma_f32 v[14:15], v[14:15], v[194:195], v[236:237]
	v_lshlrev_b32_e32 v232, 16, v225
	v_and_b32_e32 v233, s62, v225
	v_pk_fma_f32 v[16:17], v[16:17], v[232:233], v[236:237]
	v_lshlrev_b32_e32 v194, 16, v226
	v_and_b32_e32 v195, s62, v226
	v_pk_fma_f32 v[10:11], v[10:11], v[194:195], v[236:237]
	v_lshlrev_b32_e32 v232, 16, v227
	v_and_b32_e32 v233, s62, v227
	v_pk_fma_f32 v[12:13], v[12:13], v[232:233], v[236:237]
	v_cvt_pk_bf16_f32 v14, v14, v15
	v_cvt_pk_bf16_f32 v15, v16, v17
	v_cvt_pk_bf16_f32 v16, v10, v11
	v_cvt_pk_bf16_f32 v17, v12, v13
	s_waitcnt vmcnt(14)
	v_lshlrev_b32_e32 v194, 16, v228
	v_and_b32_e32 v195, s62, v228
	v_pk_fma_f32 v[6:7], v[6:7], v[194:195], v[236:237]
	v_lshlrev_b32_e32 v232, 16, v229
	v_and_b32_e32 v233, s62, v229
	v_pk_fma_f32 v[8:9], v[8:9], v[232:233], v[236:237]
	v_lshlrev_b32_e32 v194, 16, v230
	v_and_b32_e32 v195, s62, v230
	v_pk_fma_f32 v[2:3], v[2:3], v[194:195], v[236:237]
	v_lshlrev_b32_e32 v232, 16, v231
	v_and_b32_e32 v233, s62, v231
	v_pk_fma_f32 v[4:5], v[4:5], v[232:233], v[236:237]
	v_cvt_pk_bf16_f32 v6, v6, v7
	v_cvt_pk_bf16_f32 v7, v8, v9
	v_cvt_pk_bf16_f32 v8, v2, v3
	v_cvt_pk_bf16_f32 v9, v4, v5
	s_add_u32 s42, s8, 0x58000
	s_addc_u32 s43, s9, 0
	global_store_dwordx4 v139, v[14:17], s[42:43]
	global_store_dwordx4 v139, v[6:9], s[42:43] offset:256

.LBB0_891:
	s_lshl_b64 s[24:25], s[26:27], 2
	s_add_u32 s24, s30, s24
	s_addc_u32 s25, s31, s25
	s_add_u32 s24, s24, 0x2000
	s_addc_u32 s25, s25, 0
	v_mbcnt_lo_u32_b32 v143, -1, 0
	v_mbcnt_hi_u32_b32 v143, -1, v143
	v_and_b32_e32 v142, 3, v143
	v_lshrrev_b32_e32 v143, 2, v143
	v_lshl_add_u32 v160, v142, 4, v143
	v_lshlrev_b32_e32 v160, 2, v160
	v_readfirstlane_b32 s28, v140
	v_add_u32_e32 v143, s54, v143
	v_lshl_add_u32 v142, v142, 2, s28
	v_lshlrev_b32_e32 v142, 2, v142
	v_lshl_add_u32 v143, v143, 12, v142
	global_load_dwordx4 v[212:215], v142, s[24:25]
	global_load_dwordx4 v[216:219], v142, s[24:25] offset:64
	global_load_dwordx4 v[220:223], v142, s[24:25] offset:512
	global_load_dwordx4 v[224:227], v142, s[24:25] offset:576
	s_add_u32 s28, s20, 0x0
	s_addc_u32 s29, s21, 0
	global_load_dwordx4 v[144:147], v143, s[28:29]
	global_load_dwordx4 v[148:151], v143, s[28:29] offset:64
	global_load_dwordx4 v[152:155], v143, s[28:29] offset:512
	global_load_dwordx4 v[156:159], v143, s[28:29] offset:576
	s_add_u32 s28, s20, 0x10000
	s_addc_u32 s29, s21, 0
	global_load_dwordx4 v[168:171], v143, s[28:29]
	global_load_dwordx4 v[172:175], v143, s[28:29] offset:64
	global_load_dwordx4 v[176:179], v143, s[28:29] offset:512
	global_load_dwordx4 v[186:189], v143, s[28:29] offset:576
	s_add_u32 s28, s20, 0x20000
	s_addc_u32 s29, s21, 0
	global_load_dwordx4 v[190:193], v143, s[28:29]
	global_load_dwordx4 v[228:231], v143, s[28:29] offset:64
	global_load_dwordx4 v[232:235], v143, s[28:29] offset:512
	global_load_dwordx4 v[236:239], v143, s[28:29] offset:576
	s_add_u32 s28, s20, 0x30000
	s_addc_u32 s29, s21, 0
	global_load_dwordx4 v[240:243], v143, s[28:29]
	global_load_dwordx4 v[244:247], v143, s[28:29] offset:64
	global_load_dwordx4 v[248:251], v143, s[28:29] offset:512
	global_load_dwordx4 v[130:133], v143, s[28:29] offset:576
	ds_bpermute_b32 v2, v160, v2
	ds_bpermute_b32 v3, v160, v3
	ds_bpermute_b32 v4, v160, v4
	ds_bpermute_b32 v5, v160, v5
	ds_bpermute_b32 v6, v160, v6
	ds_bpermute_b32 v7, v160, v7
	ds_bpermute_b32 v8, v160, v8
	s_waitcnt lgkmcnt(7)
	ds_bpermute_b32 v9, v160, v9
	ds_bpermute_b32 v10, v160, v10
	ds_bpermute_b32 v11, v160, v11
	ds_bpermute_b32 v12, v160, v12
	ds_bpermute_b32 v13, v160, v13
	ds_bpermute_b32 v14, v160, v14
	ds_bpermute_b32 v15, v160, v15
	s_waitcnt lgkmcnt(7)
	ds_bpermute_b32 v16, v160, v16
	ds_bpermute_b32 v17, v160, v17
	ds_bpermute_b32 v18, v160, v18
	ds_bpermute_b32 v19, v160, v19
	ds_bpermute_b32 v20, v160, v20
	ds_bpermute_b32 v21, v160, v21
	ds_bpermute_b32 v22, v160, v22
	s_waitcnt lgkmcnt(7)
	ds_bpermute_b32 v23, v160, v23
	ds_bpermute_b32 v24, v160, v24
	ds_bpermute_b32 v25, v160, v25
	ds_bpermute_b32 v26, v160, v26
	ds_bpermute_b32 v27, v160, v27
	ds_bpermute_b32 v28, v160, v28
	ds_bpermute_b32 v29, v160, v29
	s_waitcnt lgkmcnt(7)
	ds_bpermute_b32 v30, v160, v30
	ds_bpermute_b32 v31, v160, v31
	ds_bpermute_b32 v32, v160, v32
	ds_bpermute_b32 v33, v160, v33
	ds_bpermute_b32 v34, v160, v34
	ds_bpermute_b32 v35, v160, v35
	ds_bpermute_b32 v36, v160, v36
	s_waitcnt lgkmcnt(7)
	ds_bpermute_b32 v37, v160, v37
	ds_bpermute_b32 v38, v160, v38
	ds_bpermute_b32 v39, v160, v39
	ds_bpermute_b32 v40, v160, v40
	ds_bpermute_b32 v41, v160, v41
	ds_bpermute_b32 v42, v160, v42
	ds_bpermute_b32 v43, v160, v43
	s_waitcnt lgkmcnt(7)
	ds_bpermute_b32 v44, v160, v44
	ds_bpermute_b32 v45, v160, v45
	ds_bpermute_b32 v46, v160, v46
	ds_bpermute_b32 v47, v160, v47
	ds_bpermute_b32 v48, v160, v48
	ds_bpermute_b32 v49, v160, v49
	ds_bpermute_b32 v50, v160, v50
	s_waitcnt lgkmcnt(7)
	ds_bpermute_b32 v51, v160, v51
	ds_bpermute_b32 v52, v160, v52
	ds_bpermute_b32 v53, v160, v53
	ds_bpermute_b32 v54, v160, v54
	ds_bpermute_b32 v55, v160, v55
	ds_bpermute_b32 v56, v160, v56
	ds_bpermute_b32 v57, v160, v57
	s_waitcnt lgkmcnt(7)
	ds_bpermute_b32 v58, v160, v58
	ds_bpermute_b32 v59, v160, v59
	ds_bpermute_b32 v60, v160, v60
	ds_bpermute_b32 v61, v160, v61
	ds_bpermute_b32 v62, v160, v62
	ds_bpermute_b32 v63, v160, v63
	ds_bpermute_b32 v64, v160, v64
	s_waitcnt lgkmcnt(7)
	ds_bpermute_b32 v65, v160, v65
	ds_bpermute_b32 v66, v160, v66
	ds_bpermute_b32 v67, v160, v67
	ds_bpermute_b32 v68, v160, v68
	ds_bpermute_b32 v69, v160, v69
	ds_bpermute_b32 v70, v160, v70
	ds_bpermute_b32 v71, v160, v71
	s_waitcnt lgkmcnt(7)
	ds_bpermute_b32 v72, v160, v72
	ds_bpermute_b32 v73, v160, v73
	ds_bpermute_b32 v74, v160, v74
	ds_bpermute_b32 v75, v160, v75
	ds_bpermute_b32 v76, v160, v76
	ds_bpermute_b32 v77, v160, v77
	ds_bpermute_b32 v78, v160, v78
	s_waitcnt lgkmcnt(7)
	ds_bpermute_b32 v79, v160, v79
	ds_bpermute_b32 v80, v160, v80
	ds_bpermute_b32 v81, v160, v81
	ds_bpermute_b32 v82, v160, v82
	ds_bpermute_b32 v83, v160, v83
	ds_bpermute_b32 v84, v160, v84
	ds_bpermute_b32 v85, v160, v85
	s_waitcnt lgkmcnt(7)
	ds_bpermute_b32 v86, v160, v86
	ds_bpermute_b32 v87, v160, v87
	ds_bpermute_b32 v88, v160, v88
	ds_bpermute_b32 v89, v160, v89
	ds_bpermute_b32 v90, v160, v90
	ds_bpermute_b32 v91, v160, v91
	ds_bpermute_b32 v92, v160, v92
	s_waitcnt lgkmcnt(7)
	ds_bpermute_b32 v93, v160, v93
	ds_bpermute_b32 v94, v160, v94
	ds_bpermute_b32 v95, v160, v95
	ds_bpermute_b32 v96, v160, v96
	ds_bpermute_b32 v97, v160, v97
	ds_bpermute_b32 v98, v160, v98
	ds_bpermute_b32 v99, v160, v99
	s_waitcnt lgkmcnt(7)
	ds_bpermute_b32 v100, v160, v100
	ds_bpermute_b32 v101, v160, v101
	ds_bpermute_b32 v102, v160, v102
	ds_bpermute_b32 v103, v160, v103
	ds_bpermute_b32 v104, v160, v104
	ds_bpermute_b32 v105, v160, v105
	ds_bpermute_b32 v106, v160, v106
	s_waitcnt lgkmcnt(7)
	ds_bpermute_b32 v107, v160, v107
	ds_bpermute_b32 v108, v160, v108
	ds_bpermute_b32 v109, v160, v109
	ds_bpermute_b32 v110, v160, v110
	ds_bpermute_b32 v111, v160, v111
	ds_bpermute_b32 v112, v160, v112
	ds_bpermute_b32 v113, v160, v113
	s_waitcnt lgkmcnt(7)
	ds_bpermute_b32 v114, v160, v114
	ds_bpermute_b32 v115, v160, v115
	ds_bpermute_b32 v116, v160, v116
	ds_bpermute_b32 v117, v160, v117
	ds_bpermute_b32 v118, v160, v118
	ds_bpermute_b32 v119, v160, v119
	ds_bpermute_b32 v120, v160, v120
	s_waitcnt lgkmcnt(7)
	ds_bpermute_b32 v121, v160, v121
	ds_bpermute_b32 v122, v160, v122
	ds_bpermute_b32 v123, v160, v123
	ds_bpermute_b32 v124, v160, v124
	ds_bpermute_b32 v125, v160, v125
	ds_bpermute_b32 v126, v160, v126
	ds_bpermute_b32 v127, v160, v127
	s_waitcnt lgkmcnt(7)
	ds_bpermute_b32 v128, v160, v128
	ds_bpermute_b32 v129, v160, v129
	s_waitcnt lgkmcnt(0)
	s_waitcnt vmcnt(12)
	v_pk_fma_f32 v[126:127], v[126:127], v[212:213], v[144:145]
	v_pk_fma_f32 v[128:129], v[128:129], v[214:215], v[146:147]
	v_pk_fma_f32 v[102:103], v[102:103], v[216:217], v[148:149]
	v_pk_fma_f32 v[104:105], v[104:105], v[218:219], v[150:151]
	v_pk_fma_f32 v[74:75], v[74:75], v[220:221], v[152:153]
	v_pk_fma_f32 v[76:77], v[76:77], v[222:223], v[154:155]
	v_pk_fma_f32 v[46:47], v[46:47], v[224:225], v[156:157]
	v_pk_fma_f32 v[48:49], v[48:49], v[226:227], v[158:159]
	s_add_u32 s28, s20, 0x80000
	s_addc_u32 s29, s21, 0
	global_load_dwordx4 v[144:147], v143, s[28:29]
	global_load_dwordx4 v[148:151], v143, s[28:29] offset:64
	global_load_dwordx4 v[152:155], v143, s[28:29] offset:512
	global_load_dwordx4 v[156:159], v143, s[28:29] offset:576
	s_add_u32 s24, s22, 0x0
	s_addc_u32 s25, s23, 0
	global_store_dwordx4 v143, v[126:129], s[24:25]
	global_store_dwordx4 v143, v[102:105], s[24:25] offset:64
	global_store_dwordx4 v143, v[74:77], s[24:25] offset:512
	global_store_dwordx4 v143, v[46:49], s[24:25] offset:576
	s_waitcnt vmcnt(16)
	v_pk_fma_f32 v[122:123], v[122:123], v[212:213], v[168:169]
	v_pk_fma_f32 v[124:125], v[124:125], v[214:215], v[170:171]
	v_pk_fma_f32 v[94:95], v[94:95], v[216:217], v[172:173]
	v_pk_fma_f32 v[96:97], v[96:97], v[218:219], v[174:175]
	v_pk_fma_f32 v[66:67], v[66:67], v[220:221], v[176:177]
	v_pk_fma_f32 v[68:69], v[68:69], v[222:223], v[178:179]
	v_pk_fma_f32 v[38:39], v[38:39], v[224:225], v[186:187]
	v_pk_fma_f32 v[40:41], v[40:41], v[226:227], v[188:189]
	s_add_u32 s28, s20, 0x90000
	s_addc_u32 s29, s21, 0
	global_load_dwordx4 v[168:171], v143, s[28:29]
	global_load_dwordx4 v[172:175], v143, s[28:29] offset:64
	global_load_dwordx4 v[176:179], v143, s[28:29] offset:512
	global_load_dwordx4 v[186:189], v143, s[28:29] offset:576
	s_add_u32 s24, s22, 0x10000
	s_addc_u32 s25, s23, 0
	global_store_dwordx4 v143, v[122:125], s[24:25]
	global_store_dwordx4 v143, v[94:97], s[24:25] offset:64
	global_store_dwordx4 v143, v[66:69], s[24:25] offset:512
	global_store_dwordx4 v143, v[38:41], s[24:25] offset:576
	s_waitcnt vmcnt(20)
	v_pk_fma_f32 v[118:119], v[118:119], v[212:213], v[190:191]
	v_pk_fma_f32 v[120:121], v[120:121], v[214:215], v[192:193]
	v_pk_fma_f32 v[90:91], v[90:91], v[216:217], v[228:229]
	v_pk_fma_f32 v[92:93], v[92:93], v[218:219], v[230:231]
	v_pk_fma_f32 v[58:59], v[58:59], v[220:221], v[232:233]
	v_pk_fma_f32 v[60:61], v[60:61], v[222:223], v[234:235]
	v_pk_fma_f32 v[30:31], v[30:31], v[224:225], v[236:237]
	v_pk_fma_f32 v[32:33], v[32:33], v[226:227], v[238:239]
	s_add_u32 s28, s20, 0xa0000
	s_addc_u32 s29, s21, 0
	global_load_dwordx4 v[190:193], v143, s[28:29]
	global_load_dwordx4 v[228:231], v143, s[28:29] offset:64
	global_load_dwordx4 v[232:235], v143, s[28:29] offset:512
	global_load_dwordx4 v[236:239], v143, s[28:29] offset:576
	s_add_u32 s24, s22, 0x20000
	s_addc_u32 s25, s23, 0
	global_store_dwordx4 v143, v[118:121], s[24:25]
	global_store_dwordx4 v143, v[90:93], s[24:25] offset:64
	global_store_dwordx4 v143, v[58:61], s[24:25] offset:512
	global_store_dwordx4 v143, v[30:33], s[24:25] offset:576
	s_waitcnt vmcnt(24)
	v_pk_fma_f32 v[114:115], v[114:115], v[212:213], v[240:241]
	v_pk_fma_f32 v[116:117], v[116:117], v[214:215], v[242:243]
	v_pk_fma_f32 v[86:87], v[86:87], v[216:217], v[244:245]
	v_pk_fma_f32 v[88:89], v[88:89], v[218:219], v[246:247]
	v_pk_fma_f32 v[50:51], v[50:51], v[220:221], v[248:249]
	v_pk_fma_f32 v[52:53], v[52:53], v[222:223], v[250:251]
	v_pk_fma_f32 v[22:23], v[22:23], v[224:225], v[130:131]
	v_pk_fma_f32 v[24:25], v[24:25], v[226:227], v[132:133]
	s_add_u32 s28, s20, 0xb0000
	s_addc_u32 s29, s21, 0
	global_load_dwordx4 v[240:243], v143, s[28:29]
	global_load_dwordx4 v[244:247], v143, s[28:29] offset:64
	global_load_dwordx4 v[248:251], v143, s[28:29] offset:512
	global_load_dwordx4 v[130:133], v143, s[28:29] offset:576
	s_add_u32 s24, s22, 0x30000
	s_addc_u32 s25, s23, 0
	global_store_dwordx4 v143, v[114:117], s[24:25]
	global_store_dwordx4 v143, v[86:89], s[24:25] offset:64
	global_store_dwordx4 v143, v[50:53], s[24:25] offset:512
	global_store_dwordx4 v143, v[22:25], s[24:25] offset:576
	s_waitcnt vmcnt(28)
	v_pk_fma_f32 v[110:111], v[110:111], v[212:213], v[144:145]
	v_pk_fma_f32 v[112:113], v[112:113], v[214:215], v[146:147]
	v_pk_fma_f32 v[78:79], v[78:79], v[216:217], v[148:149]
	v_pk_fma_f32 v[80:81], v[80:81], v[218:219], v[150:151]
	v_pk_fma_f32 v[42:43], v[42:43], v[220:221], v[152:153]
	v_pk_fma_f32 v[44:45], v[44:45], v[222:223], v[154:155]
	v_pk_fma_f32 v[14:15], v[14:15], v[224:225], v[156:157]
	v_pk_fma_f32 v[16:17], v[16:17], v[226:227], v[158:159]
	s_add_u32 s24, s22, 0x80000
	s_addc_u32 s25, s23, 0
	global_store_dwordx4 v143, v[110:113], s[24:25]
	global_store_dwordx4 v143, v[78:81], s[24:25] offset:64
	global_store_dwordx4 v143, v[42:45], s[24:25] offset:512
	global_store_dwordx4 v143, v[14:17], s[24:25] offset:576
	s_waitcnt vmcnt(24)
	v_pk_fma_f32 v[106:107], v[106:107], v[212:213], v[168:169]
	v_pk_fma_f32 v[108:109], v[108:109], v[214:215], v[170:171]
	v_pk_fma_f32 v[70:71], v[70:71], v[216:217], v[172:173]
	v_pk_fma_f32 v[72:73], v[72:73], v[218:219], v[174:175]
	v_pk_fma_f32 v[34:35], v[34:35], v[220:221], v[176:177]
	v_pk_fma_f32 v[36:37], v[36:37], v[222:223], v[178:179]
	v_pk_fma_f32 v[10:11], v[10:11], v[224:225], v[186:187]
	v_pk_fma_f32 v[12:13], v[12:13], v[226:227], v[188:189]
	s_add_u32 s24, s22, 0x90000
	s_addc_u32 s25, s23, 0
	global_store_dwordx4 v143, v[106:109], s[24:25]
	global_store_dwordx4 v143, v[70:73], s[24:25] offset:64
	global_store_dwordx4 v143, v[34:37], s[24:25] offset:512
	global_store_dwordx4 v143, v[10:13], s[24:25] offset:576
	s_waitcnt vmcnt(20)
	v_pk_fma_f32 v[98:99], v[98:99], v[212:213], v[190:191]
	v_pk_fma_f32 v[100:101], v[100:101], v[214:215], v[192:193]
	v_pk_fma_f32 v[62:63], v[62:63], v[216:217], v[228:229]
	v_pk_fma_f32 v[64:65], v[64:65], v[218:219], v[230:231]
	v_pk_fma_f32 v[26:27], v[26:27], v[220:221], v[232:233]
	v_pk_fma_f32 v[28:29], v[28:29], v[222:223], v[234:235]
	v_pk_fma_f32 v[6:7], v[6:7], v[224:225], v[236:237]
	v_pk_fma_f32 v[8:9], v[8:9], v[226:227], v[238:239]
	s_add_u32 s24, s22, 0xa0000
	s_addc_u32 s25, s23, 0
	global_store_dwordx4 v143, v[98:101], s[24:25]
	global_store_dwordx4 v143, v[62:65], s[24:25] offset:64
	global_store_dwordx4 v143, v[26:29], s[24:25] offset:512
	global_store_dwordx4 v143, v[6:9], s[24:25] offset:576
	s_waitcnt vmcnt(16)
	v_pk_fma_f32 v[82:83], v[82:83], v[212:213], v[240:241]
	v_pk_fma_f32 v[84:85], v[84:85], v[214:215], v[242:243]
	v_pk_fma_f32 v[54:55], v[54:55], v[216:217], v[244:245]
	v_pk_fma_f32 v[56:57], v[56:57], v[218:219], v[246:247]
	v_pk_fma_f32 v[18:19], v[18:19], v[220:221], v[248:249]
	v_pk_fma_f32 v[20:21], v[20:21], v[222:223], v[250:251]
	v_pk_fma_f32 v[2:3], v[2:3], v[224:225], v[130:131]
	v_pk_fma_f32 v[4:5], v[4:5], v[226:227], v[132:133]
	s_add_u32 s24, s22, 0xb0000
	s_addc_u32 s25, s23, 0
	global_store_dwordx4 v143, v[82:85], s[24:25]
	global_store_dwordx4 v143, v[54:57], s[24:25] offset:64
	global_store_dwordx4 v143, v[18:21], s[24:25] offset:512
	global_store_dwordx4 v143, v[2:5], s[24:25] offset:576
	s_and_b64 vcc, exec, s[42:43]
	s_mov_b64 s[20:21], -1
	s_cbranch_vccnz .LBB0_870
	s_branch .LBB0_894

.LBB0_1223:
	s_lshl_b64 s[14:15], s[20:21], 2
	s_add_u32 s14, s30, s14
	s_addc_u32 s15, s31, s15
	s_add_u32 s14, s14, 0x5000
	s_addc_u32 s15, s15, 0
	v_mbcnt_lo_u32_b32 v181, -1, 0
	v_mbcnt_hi_u32_b32 v181, -1, v181
	v_and_b32_e32 v171, 3, v181
	v_lshrrev_b32_e32 v181, 2, v181
	v_lshl_add_u32 v180, v171, 4, v181
	v_lshlrev_b32_e32 v180, 2, v180
	v_readfirstlane_b32 s22, v144
	v_add_u32_e32 v181, s43, v181
	v_lshl_add_u32 v171, v171, 2, s22
	v_lshlrev_b32_e32 v171, 2, v171
	v_lshl_add_u32 v181, v181, 12, v171
	global_load_dwordx4 v[212:215], v171, s[14:15]
	global_load_dwordx4 v[216:219], v171, s[14:15] offset:64
	global_load_dwordx4 v[220:223], v171, s[14:15] offset:512
	global_load_dwordx4 v[224:227], v171, s[14:15] offset:576
	s_add_u32 s22, s18, 0x0
	s_addc_u32 s23, s19, 0
	global_load_dwordx4 v[146:149], v181, s[22:23]
	global_load_dwordx4 v[150:153], v181, s[22:23] offset:64
	global_load_dwordx4 v[154:157], v181, s[22:23] offset:512
	global_load_dwordx4 v[158:161], v181, s[22:23] offset:576
	s_add_u32 s22, s18, 0x10000
	s_addc_u32 s23, s19, 0
	global_load_dwordx4 v[162:165], v181, s[22:23]
	global_load_dwordx4 v[172:175], v181, s[22:23] offset:64
	global_load_dwordx4 v[176:179], v181, s[22:23] offset:512
	global_load_dwordx4 v[186:189], v181, s[22:23] offset:576
	s_add_u32 s22, s18, 0x20000
	s_addc_u32 s23, s19, 0
	global_load_dwordx4 v[190:193], v181, s[22:23]
	global_load_dwordx4 v[228:231], v181, s[22:23] offset:64
	global_load_dwordx4 v[232:235], v181, s[22:23] offset:512
	global_load_dwordx4 v[236:239], v181, s[22:23] offset:576
	s_add_u32 s22, s18, 0x30000
	s_addc_u32 s23, s19, 0
	global_load_dwordx4 v[240:243], v181, s[22:23]
	global_load_dwordx4 v[244:247], v181, s[22:23] offset:64
	global_load_dwordx4 v[248:251], v181, s[22:23] offset:512
	global_load_dwordx4 v[130:133], v181, s[22:23] offset:576
	ds_bpermute_b32 v2, v180, v2
	ds_bpermute_b32 v3, v180, v3
	ds_bpermute_b32 v4, v180, v4
	ds_bpermute_b32 v5, v180, v5
	ds_bpermute_b32 v6, v180, v6
	ds_bpermute_b32 v7, v180, v7
	ds_bpermute_b32 v8, v180, v8
	s_waitcnt lgkmcnt(7)
	ds_bpermute_b32 v9, v180, v9
	ds_bpermute_b32 v10, v180, v10
	ds_bpermute_b32 v11, v180, v11
	ds_bpermute_b32 v12, v180, v12
	ds_bpermute_b32 v13, v180, v13
	ds_bpermute_b32 v14, v180, v14
	ds_bpermute_b32 v15, v180, v15
	s_waitcnt lgkmcnt(7)
	ds_bpermute_b32 v16, v180, v16
	ds_bpermute_b32 v17, v180, v17
	ds_bpermute_b32 v18, v180, v18
	ds_bpermute_b32 v19, v180, v19
	ds_bpermute_b32 v20, v180, v20
	ds_bpermute_b32 v21, v180, v21
	ds_bpermute_b32 v22, v180, v22
	s_waitcnt lgkmcnt(7)
	ds_bpermute_b32 v23, v180, v23
	ds_bpermute_b32 v24, v180, v24
	ds_bpermute_b32 v25, v180, v25
	ds_bpermute_b32 v26, v180, v26
	ds_bpermute_b32 v27, v180, v27
	ds_bpermute_b32 v28, v180, v28
	ds_bpermute_b32 v29, v180, v29
	s_waitcnt lgkmcnt(7)
	ds_bpermute_b32 v30, v180, v30
	ds_bpermute_b32 v31, v180, v31
	ds_bpermute_b32 v32, v180, v32
	ds_bpermute_b32 v33, v180, v33
	ds_bpermute_b32 v34, v180, v34
	ds_bpermute_b32 v35, v180, v35
	ds_bpermute_b32 v36, v180, v36
	s_waitcnt lgkmcnt(7)
	ds_bpermute_b32 v37, v180, v37
	ds_bpermute_b32 v38, v180, v38
	ds_bpermute_b32 v39, v180, v39
	ds_bpermute_b32 v40, v180, v40
	ds_bpermute_b32 v41, v180, v41
	ds_bpermute_b32 v42, v180, v42
	ds_bpermute_b32 v43, v180, v43
	s_waitcnt lgkmcnt(7)
	ds_bpermute_b32 v44, v180, v44
	ds_bpermute_b32 v45, v180, v45
	ds_bpermute_b32 v46, v180, v46
	ds_bpermute_b32 v47, v180, v47
	ds_bpermute_b32 v48, v180, v48
	ds_bpermute_b32 v49, v180, v49
	ds_bpermute_b32 v50, v180, v50
	s_waitcnt lgkmcnt(7)
	ds_bpermute_b32 v51, v180, v51
	ds_bpermute_b32 v52, v180, v52
	ds_bpermute_b32 v53, v180, v53
	ds_bpermute_b32 v54, v180, v54
	ds_bpermute_b32 v55, v180, v55
	ds_bpermute_b32 v56, v180, v56
	ds_bpermute_b32 v57, v180, v57
	s_waitcnt lgkmcnt(7)
	ds_bpermute_b32 v58, v180, v58
	ds_bpermute_b32 v59, v180, v59
	ds_bpermute_b32 v60, v180, v60
	ds_bpermute_b32 v61, v180, v61
	ds_bpermute_b32 v62, v180, v62
	ds_bpermute_b32 v63, v180, v63
	ds_bpermute_b32 v64, v180, v64
	s_waitcnt lgkmcnt(7)
	ds_bpermute_b32 v65, v180, v65
	ds_bpermute_b32 v66, v180, v66
	ds_bpermute_b32 v67, v180, v67
	ds_bpermute_b32 v68, v180, v68
	ds_bpermute_b32 v69, v180, v69
	ds_bpermute_b32 v70, v180, v70
	ds_bpermute_b32 v71, v180, v71
	s_waitcnt lgkmcnt(7)
	ds_bpermute_b32 v72, v180, v72
	ds_bpermute_b32 v73, v180, v73
	ds_bpermute_b32 v74, v180, v74
	ds_bpermute_b32 v75, v180, v75
	ds_bpermute_b32 v76, v180, v76
	ds_bpermute_b32 v77, v180, v77
	ds_bpermute_b32 v78, v180, v78
	s_waitcnt lgkmcnt(7)
	ds_bpermute_b32 v79, v180, v79
	ds_bpermute_b32 v80, v180, v80
	ds_bpermute_b32 v81, v180, v81
	ds_bpermute_b32 v82, v180, v82
	ds_bpermute_b32 v83, v180, v83
	ds_bpermute_b32 v84, v180, v84
	ds_bpermute_b32 v85, v180, v85
	s_waitcnt lgkmcnt(7)
	ds_bpermute_b32 v86, v180, v86
	ds_bpermute_b32 v87, v180, v87
	ds_bpermute_b32 v88, v180, v88
	ds_bpermute_b32 v89, v180, v89
	ds_bpermute_b32 v90, v180, v90
	ds_bpermute_b32 v91, v180, v91
	ds_bpermute_b32 v92, v180, v92
	s_waitcnt lgkmcnt(7)
	ds_bpermute_b32 v93, v180, v93
	ds_bpermute_b32 v94, v180, v94
	ds_bpermute_b32 v95, v180, v95
	ds_bpermute_b32 v96, v180, v96
	ds_bpermute_b32 v97, v180, v97
	ds_bpermute_b32 v98, v180, v98
	ds_bpermute_b32 v99, v180, v99
	s_waitcnt lgkmcnt(7)
	ds_bpermute_b32 v100, v180, v100
	ds_bpermute_b32 v101, v180, v101
	ds_bpermute_b32 v102, v180, v102
	ds_bpermute_b32 v103, v180, v103
	ds_bpermute_b32 v104, v180, v104
	ds_bpermute_b32 v105, v180, v105
	ds_bpermute_b32 v106, v180, v106
	s_waitcnt lgkmcnt(7)
	ds_bpermute_b32 v107, v180, v107
	ds_bpermute_b32 v108, v180, v108
	ds_bpermute_b32 v109, v180, v109
	ds_bpermute_b32 v110, v180, v110
	ds_bpermute_b32 v111, v180, v111
	ds_bpermute_b32 v112, v180, v112
	ds_bpermute_b32 v113, v180, v113
	s_waitcnt lgkmcnt(7)
	ds_bpermute_b32 v114, v180, v114
	ds_bpermute_b32 v115, v180, v115
	ds_bpermute_b32 v116, v180, v116
	ds_bpermute_b32 v117, v180, v117
	ds_bpermute_b32 v118, v180, v118
	ds_bpermute_b32 v119, v180, v119
	ds_bpermute_b32 v120, v180, v120
	s_waitcnt lgkmcnt(7)
	ds_bpermute_b32 v121, v180, v121
	ds_bpermute_b32 v122, v180, v122
	ds_bpermute_b32 v123, v180, v123
	ds_bpermute_b32 v124, v180, v124
	ds_bpermute_b32 v125, v180, v125
	ds_bpermute_b32 v126, v180, v126
	ds_bpermute_b32 v127, v180, v127
	s_waitcnt lgkmcnt(7)
	ds_bpermute_b32 v128, v180, v128
	ds_bpermute_b32 v129, v180, v129
	s_waitcnt lgkmcnt(0)
	s_waitcnt vmcnt(12)
	v_pk_fma_f32 v[126:127], v[126:127], v[212:213], v[146:147]
	v_pk_fma_f32 v[128:129], v[128:129], v[214:215], v[148:149]
	v_pk_fma_f32 v[98:99], v[98:99], v[216:217], v[150:151]
	v_pk_fma_f32 v[100:101], v[100:101], v[218:219], v[152:153]
	v_pk_fma_f32 v[66:67], v[66:67], v[220:221], v[154:155]
	v_pk_fma_f32 v[68:69], v[68:69], v[222:223], v[156:157]
	v_pk_fma_f32 v[38:39], v[38:39], v[224:225], v[158:159]
	v_pk_fma_f32 v[40:41], v[40:41], v[226:227], v[160:161]
	s_add_u32 s22, s18, 0x80000
	s_addc_u32 s23, s19, 0
	global_load_dwordx4 v[146:149], v181, s[22:23]
	global_load_dwordx4 v[150:153], v181, s[22:23] offset:64
	global_load_dwordx4 v[154:157], v181, s[22:23] offset:512
	global_load_dwordx4 v[158:161], v181, s[22:23] offset:576
	s_add_u32 s14, s18, 0x0
	s_addc_u32 s15, s19, 0
	global_store_dwordx4 v181, v[126:129], s[14:15]
	global_store_dwordx4 v181, v[98:101], s[14:15] offset:64
	global_store_dwordx4 v181, v[66:69], s[14:15] offset:512
	global_store_dwordx4 v181, v[38:41], s[14:15] offset:576
	s_waitcnt vmcnt(16)
	v_pk_fma_f32 v[122:123], v[122:123], v[212:213], v[162:163]
	v_pk_fma_f32 v[124:125], v[124:125], v[214:215], v[164:165]
	v_pk_fma_f32 v[94:95], v[94:95], v[216:217], v[172:173]
	v_pk_fma_f32 v[96:97], v[96:97], v[218:219], v[174:175]
	v_pk_fma_f32 v[62:63], v[62:63], v[220:221], v[176:177]
	v_pk_fma_f32 v[64:65], v[64:65], v[222:223], v[178:179]
	v_pk_fma_f32 v[30:31], v[30:31], v[224:225], v[186:187]
	v_pk_fma_f32 v[32:33], v[32:33], v[226:227], v[188:189]
	s_add_u32 s22, s18, 0x90000
	s_addc_u32 s23, s19, 0
	global_load_dwordx4 v[162:165], v181, s[22:23]
	global_load_dwordx4 v[172:175], v181, s[22:23] offset:64
	global_load_dwordx4 v[176:179], v181, s[22:23] offset:512
	global_load_dwordx4 v[186:189], v181, s[22:23] offset:576
	s_add_u32 s14, s18, 0x10000
	s_addc_u32 s15, s19, 0
	global_store_dwordx4 v181, v[122:125], s[14:15]
	global_store_dwordx4 v181, v[94:97], s[14:15] offset:64
	global_store_dwordx4 v181, v[62:65], s[14:15] offset:512
	global_store_dwordx4 v181, v[30:33], s[14:15] offset:576
	s_waitcnt vmcnt(20)
	v_pk_fma_f32 v[118:119], v[118:119], v[212:213], v[190:191]
	v_pk_fma_f32 v[120:121], v[120:121], v[214:215], v[192:193]
	v_pk_fma_f32 v[86:87], v[86:87], v[216:217], v[228:229]
	v_pk_fma_f32 v[88:89], v[88:89], v[218:219], v[230:231]
	v_pk_fma_f32 v[54:55], v[54:55], v[220:221], v[232:233]
	v_pk_fma_f32 v[56:57], v[56:57], v[222:223], v[234:235]
	v_pk_fma_f32 v[22:23], v[22:23], v[224:225], v[236:237]
	v_pk_fma_f32 v[24:25], v[24:25], v[226:227], v[238:239]
	s_add_u32 s22, s18, 0xa0000
	s_addc_u32 s23, s19, 0
	global_load_dwordx4 v[190:193], v181, s[22:23]
	global_load_dwordx4 v[228:231], v181, s[22:23] offset:64
	global_load_dwordx4 v[232:235], v181, s[22:23] offset:512
	global_load_dwordx4 v[236:239], v181, s[22:23] offset:576
	s_add_u32 s14, s18, 0x20000
	s_addc_u32 s15, s19, 0
	global_store_dwordx4 v181, v[118:121], s[14:15]
	global_store_dwordx4 v181, v[86:89], s[14:15] offset:64
	global_store_dwordx4 v181, v[54:57], s[14:15] offset:512
	global_store_dwordx4 v181, v[22:25], s[14:15] offset:576
	s_waitcnt vmcnt(24)
	v_pk_fma_f32 v[114:115], v[114:115], v[212:213], v[240:241]
	v_pk_fma_f32 v[116:117], v[116:117], v[214:215], v[242:243]
	v_pk_fma_f32 v[82:83], v[82:83], v[216:217], v[244:245]
	v_pk_fma_f32 v[84:85], v[84:85], v[218:219], v[246:247]
	v_pk_fma_f32 v[50:51], v[50:51], v[220:221], v[248:249]
	v_pk_fma_f32 v[52:53], v[52:53], v[222:223], v[250:251]
	v_pk_fma_f32 v[18:19], v[18:19], v[224:225], v[130:131]
	v_pk_fma_f32 v[20:21], v[20:21], v[226:227], v[132:133]
	s_add_u32 s22, s18, 0xb0000
	s_addc_u32 s23, s19, 0
	global_load_dwordx4 v[240:243], v181, s[22:23]
	global_load_dwordx4 v[244:247], v181, s[22:23] offset:64
	global_load_dwordx4 v[248:251], v181, s[22:23] offset:512
	global_load_dwordx4 v[130:133], v181, s[22:23] offset:576
	s_add_u32 s14, s18, 0x30000
	s_addc_u32 s15, s19, 0
	global_store_dwordx4 v181, v[114:117], s[14:15]
	global_store_dwordx4 v181, v[82:85], s[14:15] offset:64
	global_store_dwordx4 v181, v[50:53], s[14:15] offset:512
	global_store_dwordx4 v181, v[18:21], s[14:15] offset:576
	s_waitcnt vmcnt(28)
	v_pk_fma_f32 v[110:111], v[110:111], v[212:213], v[146:147]
	v_pk_fma_f32 v[112:113], v[112:113], v[214:215], v[148:149]
	v_pk_fma_f32 v[78:79], v[78:79], v[216:217], v[150:151]
	v_pk_fma_f32 v[80:81], v[80:81], v[218:219], v[152:153]
	v_pk_fma_f32 v[46:47], v[46:47], v[220:221], v[154:155]
	v_pk_fma_f32 v[48:49], v[48:49], v[222:223], v[156:157]
	v_pk_fma_f32 v[14:15], v[14:15], v[224:225], v[158:159]
	v_pk_fma_f32 v[16:17], v[16:17], v[226:227], v[160:161]
	s_add_u32 s14, s18, 0x80000
	s_addc_u32 s15, s19, 0
	global_store_dwordx4 v181, v[110:113], s[14:15]
	global_store_dwordx4 v181, v[78:81], s[14:15] offset:64
	global_store_dwordx4 v181, v[46:49], s[14:15] offset:512
	global_store_dwordx4 v181, v[14:17], s[14:15] offset:576
	s_waitcnt vmcnt(24)
	v_pk_fma_f32 v[106:107], v[106:107], v[212:213], v[162:163]
	v_pk_fma_f32 v[108:109], v[108:109], v[214:215], v[164:165]
	v_pk_fma_f32 v[74:75], v[74:75], v[216:217], v[172:173]
	v_pk_fma_f32 v[76:77], v[76:77], v[218:219], v[174:175]
	v_pk_fma_f32 v[42:43], v[42:43], v[220:221], v[176:177]
	v_pk_fma_f32 v[44:45], v[44:45], v[222:223], v[178:179]
	v_pk_fma_f32 v[10:11], v[10:11], v[224:225], v[186:187]
	v_pk_fma_f32 v[12:13], v[12:13], v[226:227], v[188:189]
	s_add_u32 s14, s18, 0x90000
	s_addc_u32 s15, s19, 0
	global_store_dwordx4 v181, v[106:109], s[14:15]
	global_store_dwordx4 v181, v[74:77], s[14:15] offset:64
	global_store_dwordx4 v181, v[42:45], s[14:15] offset:512
	global_store_dwordx4 v181, v[10:13], s[14:15] offset:576
	s_waitcnt vmcnt(20)
	v_pk_fma_f32 v[102:103], v[102:103], v[212:213], v[190:191]
	v_pk_fma_f32 v[104:105], v[104:105], v[214:215], v[192:193]
	v_pk_fma_f32 v[70:71], v[70:71], v[216:217], v[228:229]
	v_pk_fma_f32 v[72:73], v[72:73], v[218:219], v[230:231]
	v_pk_fma_f32 v[34:35], v[34:35], v[220:221], v[232:233]
	v_pk_fma_f32 v[36:37], v[36:37], v[222:223], v[234:235]
	v_pk_fma_f32 v[6:7], v[6:7], v[224:225], v[236:237]
	v_pk_fma_f32 v[8:9], v[8:9], v[226:227], v[238:239]
	s_add_u32 s14, s18, 0xa0000
	s_addc_u32 s15, s19, 0
	global_store_dwordx4 v181, v[102:105], s[14:15]
	global_store_dwordx4 v181, v[70:73], s[14:15] offset:64
	global_store_dwordx4 v181, v[34:37], s[14:15] offset:512
	global_store_dwordx4 v181, v[6:9], s[14:15] offset:576
	s_waitcnt vmcnt(16)
	v_pk_fma_f32 v[90:91], v[90:91], v[212:213], v[240:241]
	v_pk_fma_f32 v[92:93], v[92:93], v[214:215], v[242:243]
	v_pk_fma_f32 v[58:59], v[58:59], v[216:217], v[244:245]
	v_pk_fma_f32 v[60:61], v[60:61], v[218:219], v[246:247]
	v_pk_fma_f32 v[26:27], v[26:27], v[220:221], v[248:249]
	v_pk_fma_f32 v[28:29], v[28:29], v[222:223], v[250:251]
	v_pk_fma_f32 v[2:3], v[2:3], v[224:225], v[130:131]
	v_pk_fma_f32 v[4:5], v[4:5], v[226:227], v[132:133]
	s_add_u32 s14, s18, 0xb0000
	s_addc_u32 s15, s19, 0
	global_store_dwordx4 v181, v[90:93], s[14:15]
	global_store_dwordx4 v181, v[58:61], s[14:15] offset:64
	global_store_dwordx4 v181, v[26:29], s[14:15] offset:512
	global_store_dwordx4 v181, v[2:5], s[14:15] offset:576
	s_and_b64 vcc, exec, s[40:41]
	s_mov_b64 s[14:15], -1
	s_cbranch_vccnz .LBB0_1202
	s_branch .LBB0_1226
